# K-loop MFMA order variant 16_pair_a (+ load segments without VALU copies)
# baseline (speedup 1.0000x reference)
; #define PG8_STAGE(bufoff, gbase, voff) do { const char* gb_ = (const char*)(gbase); asm volatile("" : "+s"(gb_)); _Pragma("unroll") for (int _i = 0; _i < 2; ++_i) { unsigned vo_ = (voff)[_i]; asm volatile("" : "+v"(vo_));        \
;         __builtin_amdgcn_global_load_lds((const unsigned*)(gb_ + vo_), (PG8_LAS unsigned*)(lds + (bufoff) + ldsw + _i * 8192), 16, 0, 0); } } while (0)
; #define PG8_LDA(dst, b, h) do { _Pragma("unroll") for (int m = 0; m < 4; ++m) _Pragma("unroll") for (int k = 0; k < 2; ++k) dst[m][k] = *(const PG8_LAS bf16x8*)(lds + PG8_SA(b, h) + aoff + m * 2048 + k * 1024); } while (0)
; #define PG8_LDB(dst, b, h) do { _Pragma("unroll") for (int n = 0; n < 2; ++n) _Pragma("unroll") for (int k = 0; k < 2; ++k) dst[n][k] = *(const PG8_LAS bf16x8*)(lds + PG8_SB(b, h) + boff + n * 2048 + k * 1024); } while (0)
; #define PG8_WAIT_V(n) asm volatile("s_waitcnt vmcnt(" #n ")" ::: "memory")
; #define PG8_WAIT_L(n) asm volatile("s_waitcnt lgkmcnt(" #n ")" ::: "memory")
; #define PG8_BAR __builtin_amdgcn_s_barrier()
; #define PG8_SCHED __builtin_amdgcn_sched_barrier(0)
; template <class Epi, class Sched, bool ALIGN_EPI = false, bool SP2 = false>
; __device__ __forceinline__ void gemm_phase(PG8_LAS unsigned char* lds, const Gemm g, const Sched& S, const Epi& E) {
;     ...
;             if constexpr (SP2) {
;             PG8_LDB(B0, 0, 0); PG8_LDB(B1, 0, 1); PG8_SCHED; PG8_LDA(At, 0, 0); PG8_STAGE(PG8_SA(1, 1), a1 + hstep, voffA);
;             PG8_WAIT_V(8); PG8_WAIT_L(0); PG8_BAR; PG8_MMA(0, 0, At, B0); PG8_MMA(0, 1, At, B1); PG8_BAR; PG8_SCHED;
;             PG8_LDA(At, 0, 1); PG8_STAGE(PG8_SB(0, 0), b2, voffB); PG8_STAGE(PG8_SB(0, 1), b2 + hstep, voffB); PG8_STAGE(PG8_SA(0, 0), a2, voffA);
;             PG8_WAIT_V(8); PG8_WAIT_L(0); PG8_BAR; PG8_MMA(1, 0, At, B0); PG8_MMA(1, 1, At, B1); PG8_BAR; PG8_SCHED;
;             PG8_LDB(B0, 1, 0); PG8_LDB(B1, 1, 1); PG8_SCHED; PG8_LDA(At, 1, 0); PG8_STAGE(PG8_SA(0, 1), a2 + hstep, voffA);
;             PG8_WAIT_V(8); PG8_WAIT_L(0); PG8_BAR; PG8_MMA(0, 0, At, B0); PG8_MMA(0, 1, At, B1); PG8_BAR; PG8_SCHED;
;             PG8_LDA(At, 1, 1); PG8_STAGE(PG8_SB(1, 0), b3, voffB); PG8_STAGE(PG8_SB(1, 1), b3 + hstep, voffB); PG8_STAGE(PG8_SA(1, 0), a3, voffA);
;             PG8_WAIT_V(8); PG8_WAIT_L(0); PG8_BAR; PG8_MMA(1, 0, At, B0); PG8_MMA(1, 1, At, B1); PG8_BAR; PG8_SCHED;
.LBB0_232:
	s_add_u32 s2, s0, 0x100
	s_addc_u32 s3, s1, 0
	s_cmp_eq_u32 s30, 28
	s_cselect_b32 s10, s25, s2
	s_cselect_b32 s11, s24, s3
	s_cselect_b32 s8, s27, s28
	s_cselect_b32 s9, s26, s29
	s_add_u32 s6, s10, 0x80
	s_addc_u32 s7, s11, 0
	s_add_i32 s31, 0, 0x10000
	s_add_i32 s33, 0, 0x14000
	ds_read_b128 v[66:69], v244
	ds_read_b128 v[70:73], v244 offset:1024
	ds_read_b128 v[74:77], v244 offset:2048
	ds_read_b128 v[78:81], v244 offset:3072
	ds_read_b128 v[146:149], v244 offset:16384
	ds_read_b128 v[150:153], v244 offset:17408
	ds_read_b128 v[154:157], v244 offset:18432
	ds_read_b128 v[158:161], v244 offset:19456
	s_add_u32 s0, s0, 0x80080
	s_addc_u32 s1, s1, 0
	ds_read_b128 v[178:181], v223
	ds_read_b128 v[182:185], v223 offset:1024
	ds_read_b128 v[192:195], v223 offset:2048
	ds_read_b128 v[196:199], v223 offset:3072
	ds_read_b128 v[200:203], v223 offset:4096
	ds_read_b128 v[204:207], v223 offset:5120
	ds_read_b128 v[208:211], v223 offset:6144
	ds_read_b128 v[212:215], v223 offset:7168
	s_add_i32 m0, s13, 0xc000
	s_nop 0
	global_load_lds_dwordx4 v1, s[0:1]
	s_add_i32 m0, s13, 0xe000
	s_nop 0
	global_load_lds_dwordx4 v191, s[0:1]
	s_waitcnt vmcnt(8)
	s_waitcnt lgkmcnt(0)
	s_barrier
	s_setprio 1
	s_waitcnt lgkmcnt(0)
	v_mfma_f32_16x16x32_bf16 v[142:145], v[66:69], v[178:181], v[142:145]
	v_mfma_f32_16x16x32_bf16 v[134:137], v[66:69], v[192:195], v[134:137]
	v_mfma_f32_16x16x32_bf16 v[142:145], v[70:73], v[182:185], v[142:145]
	v_mfma_f32_16x16x32_bf16 v[134:137], v[70:73], v[196:199], v[134:137]
	v_mfma_f32_16x16x32_bf16 v[138:141], v[74:77], v[178:181], v[138:141]
	v_mfma_f32_16x16x32_bf16 v[130:133], v[74:77], v[192:195], v[130:133]
	v_mfma_f32_16x16x32_bf16 v[138:141], v[78:81], v[182:185], v[138:141]
	v_mfma_f32_16x16x32_bf16 v[130:133], v[78:81], v[196:199], v[130:133]
	v_mfma_f32_16x16x32_bf16 v[126:129], v[66:69], v[200:203], v[126:129]
	v_mfma_f32_16x16x32_bf16 v[118:121], v[66:69], v[208:211], v[118:121]
	v_mfma_f32_16x16x32_bf16 v[126:129], v[70:73], v[204:207], v[126:129]
	v_mfma_f32_16x16x32_bf16 v[118:121], v[70:73], v[212:215], v[118:121]
	v_mfma_f32_16x16x32_bf16 v[122:125], v[74:77], v[200:203], v[122:125]
	v_mfma_f32_16x16x32_bf16 v[114:117], v[74:77], v[208:211], v[114:117]
	v_mfma_f32_16x16x32_bf16 v[122:125], v[78:81], v[204:207], v[122:125]
	v_mfma_f32_16x16x32_bf16 v[114:117], v[78:81], v[212:215], v[114:117]
	s_setprio 0
	s_setprio 1
	v_mfma_f32_16x16x32_bf16 v[62:65], v[146:149], v[178:181], v[62:65]
	v_mfma_f32_16x16x32_bf16 v[54:57], v[146:149], v[192:195], v[54:57]
	v_mfma_f32_16x16x32_bf16 v[62:65], v[150:153], v[182:185], v[62:65]
	v_mfma_f32_16x16x32_bf16 v[54:57], v[150:153], v[196:199], v[54:57]
	v_mfma_f32_16x16x32_bf16 v[58:61], v[154:157], v[178:181], v[58:61]
	v_mfma_f32_16x16x32_bf16 v[50:53], v[154:157], v[192:195], v[50:53]
	v_mfma_f32_16x16x32_bf16 v[58:61], v[158:161], v[182:185], v[58:61]
	v_mfma_f32_16x16x32_bf16 v[50:53], v[158:161], v[196:199], v[50:53]
	v_mfma_f32_16x16x32_bf16 v[46:49], v[146:149], v[200:203], v[46:49]
	v_mfma_f32_16x16x32_bf16 v[38:41], v[146:149], v[208:211], v[38:41]
	v_mfma_f32_16x16x32_bf16 v[46:49], v[150:153], v[204:207], v[46:49]
	v_mfma_f32_16x16x32_bf16 v[38:41], v[150:153], v[212:215], v[38:41]
	v_mfma_f32_16x16x32_bf16 v[42:45], v[154:157], v[200:203], v[42:45]
	v_mfma_f32_16x16x32_bf16 v[34:37], v[154:157], v[208:211], v[34:37]
	v_mfma_f32_16x16x32_bf16 v[42:45], v[158:161], v[204:207], v[42:45]
	v_mfma_f32_16x16x32_bf16 v[34:37], v[158:161], v[212:215], v[34:37]
	s_setprio 0
	s_barrier
	s_mov_b64 s[0:1], s[8:9]
	s_add_i32 s31, s31, s12
	ds_read_b128 v[178:181], v223 offset:16384
	ds_read_b128 v[182:185], v223 offset:17408
	ds_read_b128 v[192:195], v223 offset:18432
	ds_read_b128 v[196:199], v223 offset:19456
	ds_read_b128 v[200:203], v223 offset:20480
	ds_read_b128 v[204:207], v223 offset:21504
	ds_read_b128 v[208:211], v223 offset:22528
	ds_read_b128 v[212:215], v223 offset:23552
	s_mov_b32 m0, s31
	s_nop 0
	global_load_lds_dwordx4 v189, s[0:1]
	s_add_i32 m0, s31, 0x2000
	s_nop 0
	global_load_lds_dwordx4 v219, s[0:1]
	s_add_u32 s0, s8, 0x80000
	s_addc_u32 s1, s9, 0
	s_add_i32 s31, s33, s12
	s_mov_b32 m0, s31
	s_nop 0
	global_load_lds_dwordx4 v189, s[0:1]
	s_add_i32 m0, s31, 0x2000
	s_nop 0
	global_load_lds_dwordx4 v219, s[0:1]
	s_mov_b64 s[0:1], s[10:11]
	s_mov_b32 m0, s13
	s_nop 0
	global_load_lds_dwordx4 v1, s[0:1]
	s_mov_b32 m0, s14
	s_nop 0
	global_load_lds_dwordx4 v191, s[0:1]
	s_waitcnt vmcnt(8)
	s_waitcnt lgkmcnt(0)
	s_barrier
	s_setprio 1
	s_waitcnt lgkmcnt(0)
	v_mfma_f32_16x16x32_bf16 v[110:113], v[66:69], v[178:181], v[110:113]
	v_mfma_f32_16x16x32_bf16 v[102:105], v[66:69], v[192:195], v[102:105]
	v_mfma_f32_16x16x32_bf16 v[110:113], v[70:73], v[182:185], v[110:113]
	v_mfma_f32_16x16x32_bf16 v[102:105], v[70:73], v[196:199], v[102:105]
	v_mfma_f32_16x16x32_bf16 v[106:109], v[74:77], v[178:181], v[106:109]
	v_mfma_f32_16x16x32_bf16 v[98:101], v[74:77], v[192:195], v[98:101]
	v_mfma_f32_16x16x32_bf16 v[106:109], v[78:81], v[182:185], v[106:109]
	v_mfma_f32_16x16x32_bf16 v[98:101], v[78:81], v[196:199], v[98:101]
	v_mfma_f32_16x16x32_bf16 v[94:97], v[66:69], v[200:203], v[94:97]
	v_mfma_f32_16x16x32_bf16 v[94:97], v[70:73], v[204:207], v[94:97]
	v_mfma_f32_16x16x32_bf16 v[66:69], v[66:69], v[208:211], v[86:89]
	v_mfma_f32_16x16x32_bf16 v[66:69], v[70:73], v[212:215], v[66:69]
	v_mfma_f32_16x16x32_bf16 v[90:93], v[74:77], v[200:203], v[90:93]
	v_mfma_f32_16x16x32_bf16 v[70:73], v[74:77], v[208:211], v[82:85]
	v_mfma_f32_16x16x32_bf16 v[90:93], v[78:81], v[204:207], v[90:93]
	v_mfma_f32_16x16x32_bf16 v[70:73], v[78:81], v[212:215], v[70:73]
	s_setprio 0
	s_setprio 1
	v_mfma_f32_16x16x32_bf16 v[30:33], v[146:149], v[178:181], v[30:33]
	v_mfma_f32_16x16x32_bf16 v[22:25], v[146:149], v[192:195], v[22:25]
	v_mfma_f32_16x16x32_bf16 v[30:33], v[150:153], v[182:185], v[30:33]
	v_mfma_f32_16x16x32_bf16 v[22:25], v[150:153], v[196:199], v[22:25]
	v_mfma_f32_16x16x32_bf16 v[26:29], v[154:157], v[178:181], v[26:29]
	v_mfma_f32_16x16x32_bf16 v[18:21], v[154:157], v[192:195], v[18:21]
	v_mfma_f32_16x16x32_bf16 v[26:29], v[158:161], v[182:185], v[26:29]
	v_mfma_f32_16x16x32_bf16 v[18:21], v[158:161], v[196:199], v[18:21]
	v_mfma_f32_16x16x32_bf16 v[14:17], v[146:149], v[200:203], v[14:17]
	v_mfma_f32_16x16x32_bf16 v[6:9], v[146:149], v[208:211], v[6:9]
	v_mfma_f32_16x16x32_bf16 v[14:17], v[150:153], v[204:207], v[14:17]
	v_mfma_f32_16x16x32_bf16 v[6:9], v[150:153], v[212:215], v[6:9]
	v_mfma_f32_16x16x32_bf16 v[10:13], v[154:157], v[200:203], v[10:13]
	v_mfma_f32_16x16x32_bf16 v[2:5], v[154:157], v[208:211], v[2:5]
	v_mfma_f32_16x16x32_bf16 v[10:13], v[158:161], v[204:207], v[10:13]
	v_mfma_f32_16x16x32_bf16 v[2:5], v[158:161], v[212:215], v[2:5]
	s_setprio 0
	s_barrier
; #define PG8_STAGE(bufoff, gbase, voff) do { const char* gb_ = (const char*)(gbase); asm volatile("" : "+s"(gb_)); _Pragma("unroll") for (int _i = 0; _i < 2; ++_i) { unsigned vo_ = (voff)[_i]; asm volatile("" : "+v"(vo_));        \
;         __builtin_amdgcn_global_load_lds((const unsigned*)(gb_ + vo_), (PG8_LAS unsigned*)(lds + (bufoff) + ldsw + _i * 8192), 16, 0, 0); } } while (0)
; #define PG8_LDA(dst, b, h) do { _Pragma("unroll") for (int m = 0; m < 4; ++m) _Pragma("unroll") for (int k = 0; k < 2; ++k) dst[m][k] = *(const PG8_LAS bf16x8*)(lds + PG8_SA(b, h) + aoff + m * 2048 + k * 1024); } while (0)
; #define PG8_LDB(dst, b, h) do { _Pragma("unroll") for (int n = 0; n < 2; ++n) _Pragma("unroll") for (int k = 0; k < 2; ++k) dst[n][k] = *(const PG8_LAS bf16x8*)(lds + PG8_SB(b, h) + boff + n * 2048 + k * 1024); } while (0)
; #define PG8_WAIT_V(n) asm volatile("s_waitcnt vmcnt(" #n ")" ::: "memory")
; #define PG8_WAIT_L(n) asm volatile("s_waitcnt lgkmcnt(" #n ")" ::: "memory")
; #define PG8_BAR __builtin_amdgcn_s_barrier()
; #define PG8_SCHED __builtin_amdgcn_sched_barrier(0)
; template <class Epi, class Sched, bool ALIGN_EPI = false, bool SP2 = false>
; __device__ __forceinline__ void gemm_phase(PG8_LAS unsigned char* lds, const Gemm g, const Sched& S, const Epi& E) {
;     ...
;             if constexpr (SP2) {
;             PG8_LDB(B0, 0, 0); PG8_LDB(B1, 0, 1); PG8_SCHED; PG8_LDA(At, 0, 0); PG8_STAGE(PG8_SA(1, 1), a1 + hstep, voffA);
;             PG8_WAIT_V(8); PG8_WAIT_L(0); PG8_BAR; PG8_MMA(0, 0, At, B0); PG8_MMA(0, 1, At, B1); PG8_BAR; PG8_SCHED;
;             PG8_LDA(At, 0, 1); PG8_STAGE(PG8_SB(0, 0), b2, voffB); PG8_STAGE(PG8_SB(0, 1), b2 + hstep, voffB); PG8_STAGE(PG8_SA(0, 0), a2, voffA);
;             PG8_WAIT_V(8); PG8_WAIT_L(0); PG8_BAR; PG8_MMA(1, 0, At, B0); PG8_MMA(1, 1, At, B1); PG8_BAR; PG8_SCHED;
;             PG8_LDB(B0, 1, 0); PG8_LDB(B1, 1, 1); PG8_SCHED; PG8_LDA(At, 1, 0); PG8_STAGE(PG8_SA(0, 1), a2 + hstep, voffA);
;             PG8_WAIT_V(8); PG8_WAIT_L(0); PG8_BAR; PG8_MMA(0, 0, At, B0); PG8_MMA(0, 1, At, B1); PG8_BAR; PG8_SCHED;
;             PG8_LDA(At, 1, 1); PG8_STAGE(PG8_SB(1, 0), b3, voffB); PG8_STAGE(PG8_SB(1, 1), b3 + hstep, voffB); PG8_STAGE(PG8_SA(1, 0), a3, voffA);
;             PG8_WAIT_V(8); PG8_WAIT_L(0); PG8_BAR; PG8_MMA(1, 0, At, B0); PG8_MMA(1, 1, At, B1); PG8_BAR; PG8_SCHED;
	s_add_i32 s31, 0, 0x18000
	s_add_i32 s33, 0, 0x1c000
	ds_read_b128 v[74:77], v244 offset:32768
	ds_read_b128 v[78:81], v244 offset:33792
	ds_read_b128 v[82:85], v244 offset:34816
	ds_read_b128 v[146:149], v244 offset:35840
	ds_read_b128 v[150:153], v244 offset:49152
	ds_read_b128 v[154:157], v244 offset:50176
	ds_read_b128 v[158:161], v244 offset:51200
	ds_read_b128 v[178:181], v244 offset:52224
	s_add_u32 s0, s10, 0x80000
	s_addc_u32 s1, s11, 0
	s_mov_b32 m0, s15
	ds_read_b128 v[86:89], v223 offset:32768
	ds_read_b128 v[182:185], v223 offset:33792
	ds_read_b128 v[192:195], v223 offset:34816
	ds_read_b128 v[196:199], v223 offset:35840
	ds_read_b128 v[200:203], v223 offset:36864
	ds_read_b128 v[204:207], v223 offset:37888
	ds_read_b128 v[208:211], v223 offset:38912
	ds_read_b128 v[212:215], v223 offset:39936
	s_nop 0
	global_load_lds_dwordx4 v1, s[0:1]
	s_mov_b32 m0, s16
	s_nop 0
	global_load_lds_dwordx4 v191, s[0:1]
	s_waitcnt vmcnt(8)
	s_waitcnt lgkmcnt(0)
	s_barrier
	s_setprio 1
	s_waitcnt lgkmcnt(0)
	v_mfma_f32_16x16x32_bf16 v[142:145], v[74:77], v[86:89], v[142:145]
	v_mfma_f32_16x16x32_bf16 v[134:137], v[74:77], v[192:195], v[134:137]
	v_mfma_f32_16x16x32_bf16 v[142:145], v[78:81], v[182:185], v[142:145]
	v_mfma_f32_16x16x32_bf16 v[134:137], v[78:81], v[196:199], v[134:137]
	v_mfma_f32_16x16x32_bf16 v[138:141], v[82:85], v[86:89], v[138:141]
	v_mfma_f32_16x16x32_bf16 v[130:133], v[82:85], v[192:195], v[130:133]
	v_mfma_f32_16x16x32_bf16 v[138:141], v[146:149], v[182:185], v[138:141]
	v_mfma_f32_16x16x32_bf16 v[130:133], v[146:149], v[196:199], v[130:133]
	v_mfma_f32_16x16x32_bf16 v[126:129], v[74:77], v[200:203], v[126:129]
	v_mfma_f32_16x16x32_bf16 v[118:121], v[74:77], v[208:211], v[118:121]
	v_mfma_f32_16x16x32_bf16 v[126:129], v[78:81], v[204:207], v[126:129]
	v_mfma_f32_16x16x32_bf16 v[118:121], v[78:81], v[212:215], v[118:121]
	v_mfma_f32_16x16x32_bf16 v[122:125], v[82:85], v[200:203], v[122:125]
	v_mfma_f32_16x16x32_bf16 v[114:117], v[82:85], v[208:211], v[114:117]
	v_mfma_f32_16x16x32_bf16 v[122:125], v[146:149], v[204:207], v[122:125]
	v_mfma_f32_16x16x32_bf16 v[114:117], v[146:149], v[212:215], v[114:117]
	s_setprio 0
	s_setprio 1
	v_mfma_f32_16x16x32_bf16 v[62:65], v[150:153], v[86:89], v[62:65]
	v_mfma_f32_16x16x32_bf16 v[54:57], v[150:153], v[192:195], v[54:57]
	v_mfma_f32_16x16x32_bf16 v[62:65], v[154:157], v[182:185], v[62:65]
	v_mfma_f32_16x16x32_bf16 v[54:57], v[154:157], v[196:199], v[54:57]
	v_mfma_f32_16x16x32_bf16 v[58:61], v[158:161], v[86:89], v[58:61]
	v_mfma_f32_16x16x32_bf16 v[50:53], v[158:161], v[192:195], v[50:53]
	v_mfma_f32_16x16x32_bf16 v[58:61], v[178:181], v[182:185], v[58:61]
	v_mfma_f32_16x16x32_bf16 v[50:53], v[178:181], v[196:199], v[50:53]
	v_mfma_f32_16x16x32_bf16 v[46:49], v[150:153], v[200:203], v[46:49]
	v_mfma_f32_16x16x32_bf16 v[38:41], v[150:153], v[208:211], v[38:41]
	v_mfma_f32_16x16x32_bf16 v[46:49], v[154:157], v[204:207], v[46:49]
	v_mfma_f32_16x16x32_bf16 v[38:41], v[154:157], v[212:215], v[38:41]
	v_mfma_f32_16x16x32_bf16 v[42:45], v[158:161], v[200:203], v[42:45]
	v_mfma_f32_16x16x32_bf16 v[34:37], v[158:161], v[208:211], v[34:37]
	v_mfma_f32_16x16x32_bf16 v[42:45], v[178:181], v[204:207], v[42:45]
	v_mfma_f32_16x16x32_bf16 v[34:37], v[178:181], v[212:215], v[34:37]
	s_setprio 0
	s_barrier
	s_add_u32 s0, s8, 0x80
	s_addc_u32 s1, s9, 0
	s_add_i32 s10, s31, s12
	ds_read_b128 v[182:185], v223 offset:49152
	ds_read_b128 v[192:195], v223 offset:50176
	ds_read_b128 v[196:199], v223 offset:51200
	ds_read_b128 v[200:203], v223 offset:52224
	ds_read_b128 v[204:207], v223 offset:53248
	ds_read_b128 v[208:211], v223 offset:54272
	ds_read_b128 v[212:215], v223 offset:55296
	ds_read_b128 v[224:227], v223 offset:56320
	s_mov_b32 m0, s10
	s_nop 0
	global_load_lds_dwordx4 v189, s[0:1]
	s_add_i32 m0, s10, 0x2000
	s_nop 0
	global_load_lds_dwordx4 v219, s[0:1]
	s_add_u32 s0, s8, 0x80080
	s_addc_u32 s1, s9, 0
	s_add_i32 s8, s33, s12
	s_mov_b32 m0, s8
	s_nop 0
	global_load_lds_dwordx4 v189, s[0:1]
	s_add_i32 m0, s8, 0x2000
	s_nop 0
	global_load_lds_dwordx4 v219, s[0:1]
	s_mov_b32 m0, s19
	s_nop 0
	global_load_lds_dwordx4 v1, s[6:7]
	s_mov_b32 m0, s20
	s_nop 0
	global_load_lds_dwordx4 v191, s[6:7]
	s_waitcnt vmcnt(8)
	s_waitcnt lgkmcnt(0)
	s_barrier
	s_setprio 1
	s_waitcnt lgkmcnt(0)
	v_mfma_f32_16x16x32_bf16 v[86:89], v[74:77], v[182:185], v[110:113]
	v_mfma_f32_16x16x32_bf16 v[66:69], v[74:77], v[212:215], v[66:69]
	v_mfma_f32_16x16x32_bf16 v[110:113], v[78:81], v[192:195], v[86:89]
	v_mfma_f32_16x16x32_bf16 v[86:89], v[82:85], v[182:185], v[106:109]
	v_mfma_f32_16x16x32_bf16 v[106:109], v[146:149], v[192:195], v[86:89]
	v_mfma_f32_16x16x32_bf16 v[86:89], v[74:77], v[196:199], v[102:105]
	v_mfma_f32_16x16x32_bf16 v[102:105], v[78:81], v[200:203], v[86:89]
	v_mfma_f32_16x16x32_bf16 v[86:89], v[82:85], v[196:199], v[98:101]
	v_mfma_f32_16x16x32_bf16 v[98:101], v[146:149], v[200:203], v[86:89]
	v_mfma_f32_16x16x32_bf16 v[86:89], v[74:77], v[204:207], v[94:97]
	v_mfma_f32_16x16x32_bf16 v[94:97], v[78:81], v[208:211], v[86:89]
	v_mfma_f32_16x16x32_bf16 v[86:89], v[82:85], v[204:207], v[90:93]
	v_mfma_f32_16x16x32_bf16 v[90:93], v[146:149], v[208:211], v[86:89]
	v_mfma_f32_16x16x32_bf16 v[86:89], v[78:81], v[224:227], v[66:69]
	v_mfma_f32_16x16x32_bf16 v[66:69], v[82:85], v[212:215], v[70:73]
	v_mfma_f32_16x16x32_bf16 v[82:85], v[146:149], v[224:227], v[66:69]
	s_setprio 0
	s_setprio 1
	v_mfma_f32_16x16x32_bf16 v[30:33], v[150:153], v[182:185], v[30:33]
	v_mfma_f32_16x16x32_bf16 v[22:25], v[150:153], v[196:199], v[22:25]
	v_mfma_f32_16x16x32_bf16 v[30:33], v[154:157], v[192:195], v[30:33]
	v_mfma_f32_16x16x32_bf16 v[22:25], v[154:157], v[200:203], v[22:25]
	v_mfma_f32_16x16x32_bf16 v[26:29], v[158:161], v[182:185], v[26:29]
	v_mfma_f32_16x16x32_bf16 v[18:21], v[158:161], v[196:199], v[18:21]
	v_mfma_f32_16x16x32_bf16 v[26:29], v[178:181], v[192:195], v[26:29]
	v_mfma_f32_16x16x32_bf16 v[18:21], v[178:181], v[200:203], v[18:21]
	v_mfma_f32_16x16x32_bf16 v[14:17], v[150:153], v[204:207], v[14:17]
	v_mfma_f32_16x16x32_bf16 v[6:9], v[150:153], v[212:215], v[6:9]
	v_mfma_f32_16x16x32_bf16 v[14:17], v[154:157], v[208:211], v[14:17]
	v_mfma_f32_16x16x32_bf16 v[6:9], v[154:157], v[224:227], v[6:9]
	v_mfma_f32_16x16x32_bf16 v[10:13], v[158:161], v[204:207], v[10:13]
	v_mfma_f32_16x16x32_bf16 v[2:5], v[158:161], v[212:215], v[2:5]
	v_mfma_f32_16x16x32_bf16 v[10:13], v[178:181], v[208:211], v[10:13]
	v_mfma_f32_16x16x32_bf16 v[2:5], v[178:181], v[224:227], v[2:5]
	s_setprio 0
	s_barrier
	s_add_i32 s30, s30, 2
	s_add_u32 s28, s28, 0x100
	s_addc_u32 s29, s29, 0
	s_cmp_gt_u32 s30, 29
	s_mov_b64 s[0:1], s[2:3]
	s_cbranch_scc0 .LBB0_232
	s_and_b64 vcc, exec, s[44:45]
	s_cbranch_vccz .LBB0_235
	s_barrier

; #define PG8_STAGE(bufoff, gbase, voff) do { const char* gb_ = (const char*)(gbase); asm volatile("" : "+s"(gb_)); _Pragma("unroll") for (int _i = 0; _i < 2; ++_i) { unsigned vo_ = (voff)[_i]; asm volatile("" : "+v"(vo_));        \
;         __builtin_amdgcn_global_load_lds((const unsigned*)(gb_ + vo_), (PG8_LAS unsigned*)(lds + (bufoff) + ldsw + _i * 8192), 16, 0, 0); } } while (0)
; #define PG8_LDA(dst, b, h) do { _Pragma("unroll") for (int m = 0; m < 4; ++m) _Pragma("unroll") for (int k = 0; k < 2; ++k) dst[m][k] = *(const PG8_LAS bf16x8*)(lds + PG8_SA(b, h) + aoff + m * 2048 + k * 1024); } while (0)
; #define PG8_LDB(dst, b, h) do { _Pragma("unroll") for (int n = 0; n < 2; ++n) _Pragma("unroll") for (int k = 0; k < 2; ++k) dst[n][k] = *(const PG8_LAS bf16x8*)(lds + PG8_SB(b, h) + boff + n * 2048 + k * 1024); } while (0)
; #define PG8_WAIT_V(n) asm volatile("s_waitcnt vmcnt(" #n ")" ::: "memory")
; #define PG8_WAIT_L(n) asm volatile("s_waitcnt lgkmcnt(" #n ")" ::: "memory")
; #define PG8_BAR __builtin_amdgcn_s_barrier()
; #define PG8_SCHED __builtin_amdgcn_sched_barrier(0)
; template <class Epi, class Sched, bool ALIGN_EPI = false, bool SP2 = false>
; __device__ __forceinline__ void gemm_phase(PG8_LAS unsigned char* lds, const Gemm g, const Sched& S, const Epi& E) {
;     ...
;             if constexpr (SP2) {
;             PG8_LDB(B0, 0, 0); PG8_LDB(B1, 0, 1); PG8_SCHED; PG8_LDA(At, 0, 0); PG8_STAGE(PG8_SA(1, 1), a1 + hstep, voffA);
;             PG8_WAIT_V(8); PG8_WAIT_L(0); PG8_BAR; PG8_MMA(0, 0, At, B0); PG8_MMA(0, 1, At, B1); PG8_BAR; PG8_SCHED;
;             PG8_LDA(At, 0, 1); PG8_STAGE(PG8_SB(0, 0), b2, voffB); PG8_STAGE(PG8_SB(0, 1), b2 + hstep, voffB); PG8_STAGE(PG8_SA(0, 0), a2, voffA);
;             PG8_WAIT_V(8); PG8_WAIT_L(0); PG8_BAR; PG8_MMA(1, 0, At, B0); PG8_MMA(1, 1, At, B1); PG8_BAR; PG8_SCHED;
;             PG8_LDB(B0, 1, 0); PG8_LDB(B1, 1, 1); PG8_SCHED; PG8_LDA(At, 1, 0); PG8_STAGE(PG8_SA(0, 1), a2 + hstep, voffA);
;             PG8_WAIT_V(8); PG8_WAIT_L(0); PG8_BAR; PG8_MMA(0, 0, At, B0); PG8_MMA(0, 1, At, B1); PG8_BAR; PG8_SCHED;
;             PG8_LDA(At, 1, 1); PG8_STAGE(PG8_SB(1, 0), b3, voffB); PG8_STAGE(PG8_SB(1, 1), b3 + hstep, voffB); PG8_STAGE(PG8_SA(1, 0), a3, voffA);
;             PG8_WAIT_V(8); PG8_WAIT_L(0); PG8_BAR; PG8_MMA(1, 0, At, B0); PG8_MMA(1, 1, At, B1); PG8_BAR; PG8_SCHED;
.LBB0_555:
	s_add_u32 s6, s4, 0x100
	s_addc_u32 s7, s5, 0
	s_cmp_eq_u32 s51, 28
	s_cselect_b32 s12, s35, s6
	s_cselect_b32 s13, s34, s7
	s_cselect_b32 s10, s39, s40
	s_cselect_b32 s11, s38, s49
	s_add_u32 s8, s12, 0x80
	s_addc_u32 s9, s13, 0
	s_add_i32 s56, 0, 0x10000
	s_add_i32 s57, 0, 0x14000
	ds_read_b128 v[26:29], v244
	ds_read_b128 v[30:33], v244 offset:1024
	ds_read_b128 v[98:101], v244 offset:2048
	ds_read_b128 v[102:105], v244 offset:3072
	ds_read_b128 v[146:149], v244 offset:16384
	ds_read_b128 v[150:153], v244 offset:17408
	ds_read_b128 v[154:157], v244 offset:18432
	ds_read_b128 v[158:161], v244 offset:19456
	s_add_u32 s4, s4, 0x80080
	s_addc_u32 s5, s5, 0
	ds_read_b128 v[178:181], v210
	ds_read_b128 v[182:185], v210 offset:1024
	ds_read_b128 v[186:189], v210 offset:2048
	ds_read_b128 v[190:193], v210 offset:3072
	ds_read_b128 v[194:197], v210 offset:4096
	ds_read_b128 v[198:201], v210 offset:5120
	ds_read_b128 v[202:205], v210 offset:6144
	ds_read_b128 v[212:215], v210 offset:7168
	s_add_i32 m0, s18, 0xc000
	s_nop 0
	global_load_lds_dwordx4 v1, s[4:5]
	s_add_i32 m0, s18, 0xe000
	s_nop 0
	global_load_lds_dwordx4 v164, s[4:5]
	s_waitcnt vmcnt(8)
	s_waitcnt lgkmcnt(0)
	s_barrier
	s_setprio 1
	s_waitcnt lgkmcnt(0)
	v_mfma_f32_16x16x32_bf16 v[142:145], v[26:29], v[178:181], v[142:145]
	v_mfma_f32_16x16x32_bf16 v[134:137], v[26:29], v[186:189], v[134:137]
	v_mfma_f32_16x16x32_bf16 v[142:145], v[30:33], v[182:185], v[142:145]
	v_mfma_f32_16x16x32_bf16 v[134:137], v[30:33], v[190:193], v[134:137]
	v_mfma_f32_16x16x32_bf16 v[138:141], v[98:101], v[178:181], v[138:141]
	v_mfma_f32_16x16x32_bf16 v[130:133], v[98:101], v[186:189], v[130:133]
	v_mfma_f32_16x16x32_bf16 v[138:141], v[102:105], v[182:185], v[138:141]
	v_mfma_f32_16x16x32_bf16 v[130:133], v[102:105], v[190:193], v[130:133]
	v_mfma_f32_16x16x32_bf16 v[126:129], v[26:29], v[194:197], v[126:129]
	v_mfma_f32_16x16x32_bf16 v[118:121], v[26:29], v[202:205], v[118:121]
	v_mfma_f32_16x16x32_bf16 v[126:129], v[30:33], v[198:201], v[126:129]
	v_mfma_f32_16x16x32_bf16 v[118:121], v[30:33], v[212:215], v[118:121]
	v_mfma_f32_16x16x32_bf16 v[122:125], v[98:101], v[194:197], v[122:125]
	v_mfma_f32_16x16x32_bf16 v[114:117], v[98:101], v[202:205], v[114:117]
	v_mfma_f32_16x16x32_bf16 v[122:125], v[102:105], v[198:201], v[122:125]
	v_mfma_f32_16x16x32_bf16 v[114:117], v[102:105], v[212:215], v[114:117]
	s_setprio 0
	s_setprio 1
	v_mfma_f32_16x16x32_bf16 v[70:73], v[146:149], v[178:181], v[70:73]
	v_mfma_f32_16x16x32_bf16 v[62:65], v[146:149], v[186:189], v[62:65]
	v_mfma_f32_16x16x32_bf16 v[70:73], v[150:153], v[182:185], v[70:73]
	v_mfma_f32_16x16x32_bf16 v[62:65], v[150:153], v[190:193], v[62:65]
	v_mfma_f32_16x16x32_bf16 v[66:69], v[154:157], v[178:181], v[66:69]
	v_mfma_f32_16x16x32_bf16 v[58:61], v[154:157], v[186:189], v[58:61]
	v_mfma_f32_16x16x32_bf16 v[66:69], v[158:161], v[182:185], v[66:69]
	v_mfma_f32_16x16x32_bf16 v[58:61], v[158:161], v[190:193], v[58:61]
	v_mfma_f32_16x16x32_bf16 v[54:57], v[146:149], v[194:197], v[54:57]
	v_mfma_f32_16x16x32_bf16 v[46:49], v[146:149], v[202:205], v[46:49]
	v_mfma_f32_16x16x32_bf16 v[54:57], v[150:153], v[198:201], v[54:57]
	v_mfma_f32_16x16x32_bf16 v[46:49], v[150:153], v[212:215], v[46:49]
	v_mfma_f32_16x16x32_bf16 v[50:53], v[154:157], v[194:197], v[50:53]
	v_mfma_f32_16x16x32_bf16 v[42:45], v[154:157], v[202:205], v[42:45]
	v_mfma_f32_16x16x32_bf16 v[50:53], v[158:161], v[198:201], v[50:53]
	v_mfma_f32_16x16x32_bf16 v[42:45], v[158:161], v[212:215], v[42:45]
	s_setprio 0
	s_barrier
	s_mov_b64 s[4:5], s[10:11]
	s_add_i32 s56, s56, s17
	ds_read_b128 v[178:181], v210 offset:16384
	ds_read_b128 v[182:185], v210 offset:17408
	ds_read_b128 v[186:189], v210 offset:18432
	ds_read_b128 v[190:193], v210 offset:19456
	ds_read_b128 v[194:197], v210 offset:20480
	ds_read_b128 v[198:201], v210 offset:21504
	ds_read_b128 v[202:205], v210 offset:22528
	ds_read_b128 v[212:215], v210 offset:23552
	s_mov_b32 m0, s56
	s_nop 0
	global_load_lds_dwordx4 v162, s[4:5]
	s_add_i32 m0, s56, 0x2000
	s_nop 0
	global_load_lds_dwordx4 v206, s[4:5]
	s_add_u32 s4, s10, 0x80000
	s_addc_u32 s5, s11, 0
	s_add_i32 s56, s57, s17
	s_mov_b32 m0, s56
	s_nop 0
	global_load_lds_dwordx4 v162, s[4:5]
	s_add_i32 m0, s56, 0x2000
	s_nop 0
	global_load_lds_dwordx4 v206, s[4:5]
	s_mov_b64 s[4:5], s[12:13]
	s_mov_b32 m0, s18
	s_nop 0
	global_load_lds_dwordx4 v1, s[4:5]
	s_mov_b32 m0, s19
	s_nop 0
	global_load_lds_dwordx4 v164, s[4:5]
	s_waitcnt vmcnt(8)
	s_waitcnt lgkmcnt(0)
	s_barrier
; #define PG8_STAGE(bufoff, gbase, voff) do { const char* gb_ = (const char*)(gbase); asm volatile("" : "+s"(gb_)); _Pragma("unroll") for (int _i = 0; _i < 2; ++_i) { unsigned vo_ = (voff)[_i]; asm volatile("" : "+v"(vo_));        \
;         __builtin_amdgcn_global_load_lds((const unsigned*)(gb_ + vo_), (PG8_LAS unsigned*)(lds + (bufoff) + ldsw + _i * 8192), 16, 0, 0); } } while (0)
; #define PG8_LDA(dst, b, h) do { _Pragma("unroll") for (int m = 0; m < 4; ++m) _Pragma("unroll") for (int k = 0; k < 2; ++k) dst[m][k] = *(const PG8_LAS bf16x8*)(lds + PG8_SA(b, h) + aoff + m * 2048 + k * 1024); } while (0)
; #define PG8_LDB(dst, b, h) do { _Pragma("unroll") for (int n = 0; n < 2; ++n) _Pragma("unroll") for (int k = 0; k < 2; ++k) dst[n][k] = *(const PG8_LAS bf16x8*)(lds + PG8_SB(b, h) + boff + n * 2048 + k * 1024); } while (0)
; #define PG8_WAIT_V(n) asm volatile("s_waitcnt vmcnt(" #n ")" ::: "memory")
; #define PG8_WAIT_L(n) asm volatile("s_waitcnt lgkmcnt(" #n ")" ::: "memory")
; #define PG8_BAR __builtin_amdgcn_s_barrier()
; #define PG8_SCHED __builtin_amdgcn_sched_barrier(0)
; template <class Epi, class Sched, bool ALIGN_EPI = false, bool SP2 = false>
; __device__ __forceinline__ void gemm_phase(PG8_LAS unsigned char* lds, const Gemm g, const Sched& S, const Epi& E) {
;     ...
;             if constexpr (SP2) {
;             PG8_LDB(B0, 0, 0); PG8_LDB(B1, 0, 1); PG8_SCHED; PG8_LDA(At, 0, 0); PG8_STAGE(PG8_SA(1, 1), a1 + hstep, voffA);
;             PG8_WAIT_V(8); PG8_WAIT_L(0); PG8_BAR; PG8_MMA(0, 0, At, B0); PG8_MMA(0, 1, At, B1); PG8_BAR; PG8_SCHED;
;             PG8_LDA(At, 0, 1); PG8_STAGE(PG8_SB(0, 0), b2, voffB); PG8_STAGE(PG8_SB(0, 1), b2 + hstep, voffB); PG8_STAGE(PG8_SA(0, 0), a2, voffA);
;             PG8_WAIT_V(8); PG8_WAIT_L(0); PG8_BAR; PG8_MMA(1, 0, At, B0); PG8_MMA(1, 1, At, B1); PG8_BAR; PG8_SCHED;
;             PG8_LDB(B0, 1, 0); PG8_LDB(B1, 1, 1); PG8_SCHED; PG8_LDA(At, 1, 0); PG8_STAGE(PG8_SA(0, 1), a2 + hstep, voffA);
;             PG8_WAIT_V(8); PG8_WAIT_L(0); PG8_BAR; PG8_MMA(0, 0, At, B0); PG8_MMA(0, 1, At, B1); PG8_BAR; PG8_SCHED;
;             PG8_LDA(At, 1, 1); PG8_STAGE(PG8_SB(1, 0), b3, voffB); PG8_STAGE(PG8_SB(1, 1), b3 + hstep, voffB); PG8_STAGE(PG8_SA(1, 0), a3, voffA);
;             PG8_WAIT_V(8); PG8_WAIT_L(0); PG8_BAR; PG8_MMA(1, 0, At, B0); PG8_MMA(1, 1, At, B1); PG8_BAR; PG8_SCHED;
	s_setprio 1
	s_waitcnt lgkmcnt(0)
	v_mfma_f32_16x16x32_bf16 v[110:113], v[26:29], v[178:181], v[110:113]
	v_mfma_f32_16x16x32_bf16 v[94:97], v[26:29], v[186:189], v[94:97]
	v_mfma_f32_16x16x32_bf16 v[110:113], v[30:33], v[182:185], v[110:113]
	v_mfma_f32_16x16x32_bf16 v[94:97], v[30:33], v[190:193], v[94:97]
	v_mfma_f32_16x16x32_bf16 v[106:109], v[98:101], v[178:181], v[106:109]
	v_mfma_f32_16x16x32_bf16 v[90:93], v[98:101], v[186:189], v[90:93]
	v_mfma_f32_16x16x32_bf16 v[106:109], v[102:105], v[182:185], v[106:109]
	v_mfma_f32_16x16x32_bf16 v[90:93], v[102:105], v[190:193], v[90:93]
	v_mfma_f32_16x16x32_bf16 v[86:89], v[26:29], v[194:197], v[86:89]
	v_mfma_f32_16x16x32_bf16 v[86:89], v[30:33], v[198:201], v[86:89]
	v_mfma_f32_16x16x32_bf16 v[26:29], v[26:29], v[202:205], v[78:81]
	v_mfma_f32_16x16x32_bf16 v[26:29], v[30:33], v[212:215], v[26:29]
	v_mfma_f32_16x16x32_bf16 v[82:85], v[98:101], v[194:197], v[82:85]
	v_mfma_f32_16x16x32_bf16 v[30:33], v[98:101], v[202:205], v[74:77]
	v_mfma_f32_16x16x32_bf16 v[82:85], v[102:105], v[198:201], v[82:85]
	v_mfma_f32_16x16x32_bf16 v[30:33], v[102:105], v[212:215], v[30:33]
	s_setprio 0
	s_setprio 1
	v_mfma_f32_16x16x32_bf16 v[38:41], v[146:149], v[178:181], v[38:41]
	v_mfma_f32_16x16x32_bf16 v[22:25], v[146:149], v[186:189], v[22:25]
	v_mfma_f32_16x16x32_bf16 v[38:41], v[150:153], v[182:185], v[38:41]
	v_mfma_f32_16x16x32_bf16 v[22:25], v[150:153], v[190:193], v[22:25]
	v_mfma_f32_16x16x32_bf16 v[34:37], v[154:157], v[178:181], v[34:37]
	v_mfma_f32_16x16x32_bf16 v[18:21], v[154:157], v[186:189], v[18:21]
	v_mfma_f32_16x16x32_bf16 v[34:37], v[158:161], v[182:185], v[34:37]
	v_mfma_f32_16x16x32_bf16 v[18:21], v[158:161], v[190:193], v[18:21]
	v_mfma_f32_16x16x32_bf16 v[14:17], v[146:149], v[194:197], v[14:17]
	v_mfma_f32_16x16x32_bf16 v[6:9], v[146:149], v[202:205], v[6:9]
	v_mfma_f32_16x16x32_bf16 v[14:17], v[150:153], v[198:201], v[14:17]
	v_mfma_f32_16x16x32_bf16 v[6:9], v[150:153], v[212:215], v[6:9]
	v_mfma_f32_16x16x32_bf16 v[10:13], v[154:157], v[194:197], v[10:13]
	v_mfma_f32_16x16x32_bf16 v[2:5], v[154:157], v[202:205], v[2:5]
	v_mfma_f32_16x16x32_bf16 v[10:13], v[158:161], v[198:201], v[10:13]
	v_mfma_f32_16x16x32_bf16 v[2:5], v[158:161], v[212:215], v[2:5]
	s_setprio 0
	s_barrier
	s_add_i32 s56, 0, 0x18000
	s_add_i32 s57, 0, 0x1c000
	ds_read_b128 v[74:77], v244 offset:32768
	ds_read_b128 v[78:81], v244 offset:33792
	ds_read_b128 v[98:101], v244 offset:34816
	ds_read_b128 v[102:105], v244 offset:35840
	ds_read_b128 v[146:149], v244 offset:49152
	ds_read_b128 v[150:153], v244 offset:50176
	ds_read_b128 v[154:157], v244 offset:51200
	ds_read_b128 v[158:161], v244 offset:52224
	s_add_u32 s4, s12, 0x80000
	s_addc_u32 s5, s13, 0
	s_mov_b32 m0, s20
	ds_read_b128 v[178:181], v210 offset:32768
	ds_read_b128 v[182:185], v210 offset:33792
	ds_read_b128 v[186:189], v210 offset:34816
	ds_read_b128 v[190:193], v210 offset:35840
	ds_read_b128 v[194:197], v210 offset:36864
	ds_read_b128 v[198:201], v210 offset:37888
	ds_read_b128 v[202:205], v210 offset:38912
	ds_read_b128 v[212:215], v210 offset:39936
	s_nop 0
	global_load_lds_dwordx4 v1, s[4:5]
	s_mov_b32 m0, s21
	s_nop 0
	global_load_lds_dwordx4 v164, s[4:5]
	s_waitcnt vmcnt(8)
	s_waitcnt lgkmcnt(0)
	s_barrier
	s_setprio 1
	s_waitcnt lgkmcnt(0)
	v_mfma_f32_16x16x32_bf16 v[142:145], v[74:77], v[178:181], v[142:145]
	v_mfma_f32_16x16x32_bf16 v[134:137], v[74:77], v[186:189], v[134:137]
	v_mfma_f32_16x16x32_bf16 v[142:145], v[78:81], v[182:185], v[142:145]
	v_mfma_f32_16x16x32_bf16 v[134:137], v[78:81], v[190:193], v[134:137]
	v_mfma_f32_16x16x32_bf16 v[138:141], v[98:101], v[178:181], v[138:141]
	v_mfma_f32_16x16x32_bf16 v[130:133], v[98:101], v[186:189], v[130:133]
	v_mfma_f32_16x16x32_bf16 v[138:141], v[102:105], v[182:185], v[138:141]
	v_mfma_f32_16x16x32_bf16 v[130:133], v[102:105], v[190:193], v[130:133]
	v_mfma_f32_16x16x32_bf16 v[126:129], v[74:77], v[194:197], v[126:129]
	v_mfma_f32_16x16x32_bf16 v[118:121], v[74:77], v[202:205], v[118:121]
	v_mfma_f32_16x16x32_bf16 v[126:129], v[78:81], v[198:201], v[126:129]
	v_mfma_f32_16x16x32_bf16 v[118:121], v[78:81], v[212:215], v[118:121]
	v_mfma_f32_16x16x32_bf16 v[122:125], v[98:101], v[194:197], v[122:125]
	v_mfma_f32_16x16x32_bf16 v[114:117], v[98:101], v[202:205], v[114:117]
	v_mfma_f32_16x16x32_bf16 v[122:125], v[102:105], v[198:201], v[122:125]
	v_mfma_f32_16x16x32_bf16 v[114:117], v[102:105], v[212:215], v[114:117]
	s_setprio 0
	s_setprio 1
	v_mfma_f32_16x16x32_bf16 v[70:73], v[146:149], v[178:181], v[70:73]
	v_mfma_f32_16x16x32_bf16 v[62:65], v[146:149], v[186:189], v[62:65]
	v_mfma_f32_16x16x32_bf16 v[70:73], v[150:153], v[182:185], v[70:73]
	v_mfma_f32_16x16x32_bf16 v[62:65], v[150:153], v[190:193], v[62:65]
	v_mfma_f32_16x16x32_bf16 v[66:69], v[154:157], v[178:181], v[66:69]
	v_mfma_f32_16x16x32_bf16 v[58:61], v[154:157], v[186:189], v[58:61]
	v_mfma_f32_16x16x32_bf16 v[66:69], v[158:161], v[182:185], v[66:69]
	v_mfma_f32_16x16x32_bf16 v[58:61], v[158:161], v[190:193], v[58:61]
	v_mfma_f32_16x16x32_bf16 v[54:57], v[146:149], v[194:197], v[54:57]
	v_mfma_f32_16x16x32_bf16 v[46:49], v[146:149], v[202:205], v[46:49]
	v_mfma_f32_16x16x32_bf16 v[54:57], v[150:153], v[198:201], v[54:57]
	v_mfma_f32_16x16x32_bf16 v[46:49], v[150:153], v[212:215], v[46:49]
	v_mfma_f32_16x16x32_bf16 v[50:53], v[154:157], v[194:197], v[50:53]
	v_mfma_f32_16x16x32_bf16 v[42:45], v[154:157], v[202:205], v[42:45]
	v_mfma_f32_16x16x32_bf16 v[50:53], v[158:161], v[198:201], v[50:53]
	v_mfma_f32_16x16x32_bf16 v[42:45], v[158:161], v[212:215], v[42:45]
	s_setprio 0
	s_barrier
;     __device__ __forceinline__ void operator()(const f32x4 (&acc)[2][2][4][2], const Unit& u, int wr, int wc, int fr, int fq) const {
;         const int row0 = u.pm * BM + wr * 64 + fr, col0 = u.pn * BM + wc * 32 + 8 * fq, b = (u.pm * BM) / rows_per_batch;
;         const float* g = gate + (size_t)b * gate_bstride + col0;
;         float ssq[2][4];
; #pragma unroll
;         for (int ai = 0; ai < 2; ++ai)
; #pragma unroll
;             for (int m = 0; m < 4; ++m) ssq[ai][m] = 0.f;
;         f32x4 gv[2][2], Gv[2][2];
; #pragma unroll
;         for (int bj = 0; bj < 2; ++bj) { gv[bj][0] = *(const f32x4*)(g + bj * HALF); gv[bj][1] = *(const f32x4*)(g + bj * HALF + 4); Gv[bj][0] = (f32x4){0.f, 0.f, 0.f, 0.f}; Gv[bj][1] = (f32x4){0.f, 0.f, 0.f, 0.f};
;             if (Hn) { const float* sc = scnext + (size_t)b * gate_bstride + col0 + bj * HALF;
;                 Gv[bj][0] = *(const f32x4*)(gnext + col0 + bj * HALF) * (1.0f + *(const f32x4*)(sc)); Gv[bj][1] = *(const f32x4*)(gnext + col0 + bj * HALF + 4) * (1.0f + *(const f32x4*)(sc + 4)); } }
; #pragma unroll
;         for (int bj = 0; bj < 2; ++bj) {
; template <class Epi, class Sched, bool ALIGN_EPI = false, bool SP2 = false>
; __device__ __forceinline__ void gemm_phase(PG8_LAS unsigned char* lds, const Gemm g, const Sched& S, const Epi& E) {
;     ...
;             if constexpr (SP2) {
;             PG8_LDB(B0, 0, 0); PG8_LDB(B1, 0, 1); PG8_SCHED; PG8_LDA(At, 0, 0); PG8_STAGE(PG8_SA(1, 1), a1 + hstep, voffA);
;             PG8_WAIT_V(8); PG8_WAIT_L(0); PG8_BAR; PG8_MMA(0, 0, At, B0); PG8_MMA(0, 1, At, B1); PG8_BAR; PG8_SCHED;
;             PG8_LDA(At, 0, 1); PG8_STAGE(PG8_SB(0, 0), b2, voffB); PG8_STAGE(PG8_SB(0, 1), b2 + hstep, voffB); PG8_STAGE(PG8_SA(0, 0), a2, voffA);
;             PG8_WAIT_V(8); PG8_WAIT_L(0); PG8_BAR; PG8_MMA(1, 0, At, B0); PG8_MMA(1, 1, At, B1); PG8_BAR; PG8_SCHED;
;             PG8_LDB(B0, 1, 0); PG8_LDB(B1, 1, 1); PG8_SCHED; PG8_LDA(At, 1, 0); PG8_STAGE(PG8_SA(0, 1), a2 + hstep, voffA);
;             PG8_WAIT_V(8); PG8_WAIT_L(0); PG8_BAR; PG8_MMA(0, 0, At, B0); PG8_MMA(0, 1, At, B1); PG8_BAR; PG8_SCHED;
;             PG8_LDA(At, 1, 1); PG8_STAGE(PG8_SB(1, 0), b3, voffB); PG8_STAGE(PG8_SB(1, 1), b3 + hstep, voffB); PG8_STAGE(PG8_SA(1, 0), a3, voffA);
;             PG8_WAIT_V(8); PG8_WAIT_L(0); PG8_BAR; PG8_MMA(1, 0, At, B0); PG8_MMA(1, 1, At, B1); PG8_BAR; PG8_SCHED;
	s_add_u32 s4, s10, 0x80
	s_addc_u32 s5, s11, 0
	s_add_i32 s12, s56, s17
	ds_read_b128 v[178:181], v210 offset:49152
	ds_read_b128 v[182:185], v210 offset:50176
	ds_read_b128 v[186:189], v210 offset:51200
	ds_read_b128 v[190:193], v210 offset:52224
	ds_read_b128 v[194:197], v210 offset:53248
	ds_read_b128 v[198:201], v210 offset:54272
	ds_read_b128 v[202:205], v210 offset:55296
	ds_read_b128 v[212:215], v210 offset:56320
	s_mov_b32 m0, s12
	s_nop 0
	global_load_lds_dwordx4 v162, s[4:5]
	s_add_i32 m0, s12, 0x2000
	s_nop 0
	global_load_lds_dwordx4 v206, s[4:5]
	s_add_u32 s4, s10, 0x80080
	s_addc_u32 s5, s11, 0
	s_add_i32 s10, s57, s17
	s_mov_b32 m0, s10
	s_nop 0
	global_load_lds_dwordx4 v162, s[4:5]
	s_add_i32 m0, s10, 0x2000
	s_nop 0
	global_load_lds_dwordx4 v206, s[4:5]
	s_mov_b32 m0, s26
	s_nop 0
	global_load_lds_dwordx4 v1, s[8:9]
	s_mov_b32 m0, s27
	s_nop 0
	global_load_lds_dwordx4 v164, s[8:9]
	s_waitcnt vmcnt(8)
	s_waitcnt lgkmcnt(0)
	s_barrier
	s_setprio 1
	s_waitcnt lgkmcnt(0)
	v_mfma_f32_16x16x32_bf16 v[110:113], v[74:77], v[178:181], v[110:113]
	v_mfma_f32_16x16x32_bf16 v[94:97], v[74:77], v[186:189], v[94:97]
	v_mfma_f32_16x16x32_bf16 v[110:113], v[78:81], v[182:185], v[110:113]
	v_mfma_f32_16x16x32_bf16 v[94:97], v[78:81], v[190:193], v[94:97]
	v_mfma_f32_16x16x32_bf16 v[86:89], v[74:77], v[194:197], v[86:89]
	v_mfma_f32_16x16x32_bf16 v[26:29], v[74:77], v[202:205], v[26:29]
	v_mfma_f32_16x16x32_bf16 v[86:89], v[78:81], v[198:201], v[86:89]
	v_mfma_f32_16x16x32_bf16 v[78:81], v[78:81], v[212:215], v[26:29]
	v_mfma_f32_16x16x32_bf16 v[106:109], v[98:101], v[178:181], v[106:109]
	v_mfma_f32_16x16x32_bf16 v[90:93], v[98:101], v[186:189], v[90:93]
	v_mfma_f32_16x16x32_bf16 v[106:109], v[102:105], v[182:185], v[106:109]
	v_mfma_f32_16x16x32_bf16 v[90:93], v[102:105], v[190:193], v[90:93]
	v_mfma_f32_16x16x32_bf16 v[82:85], v[98:101], v[194:197], v[82:85]
	v_mfma_f32_16x16x32_bf16 v[26:29], v[98:101], v[202:205], v[30:33]
	v_mfma_f32_16x16x32_bf16 v[82:85], v[102:105], v[198:201], v[82:85]
	v_mfma_f32_16x16x32_bf16 v[74:77], v[102:105], v[212:215], v[26:29]
	s_setprio 0
	s_setprio 1
	v_mfma_f32_16x16x32_bf16 v[26:29], v[146:149], v[178:181], v[38:41]
	v_mfma_f32_16x16x32_bf16 v[22:25], v[146:149], v[186:189], v[22:25]
	v_mfma_f32_16x16x32_bf16 v[38:41], v[150:153], v[182:185], v[26:29]
	v_mfma_f32_16x16x32_bf16 v[22:25], v[150:153], v[190:193], v[22:25]
	v_mfma_f32_16x16x32_bf16 v[26:29], v[154:157], v[178:181], v[34:37]
	v_mfma_f32_16x16x32_bf16 v[18:21], v[154:157], v[186:189], v[18:21]
	v_mfma_f32_16x16x32_bf16 v[34:37], v[158:161], v[182:185], v[26:29]
	v_mfma_f32_16x16x32_bf16 v[18:21], v[158:161], v[190:193], v[18:21]
	v_mfma_f32_16x16x32_bf16 v[14:17], v[146:149], v[194:197], v[14:17]
	v_mfma_f32_16x16x32_bf16 v[6:9], v[146:149], v[202:205], v[6:9]
	v_mfma_f32_16x16x32_bf16 v[14:17], v[150:153], v[198:201], v[14:17]
	v_mfma_f32_16x16x32_bf16 v[6:9], v[150:153], v[212:215], v[6:9]
	v_mfma_f32_16x16x32_bf16 v[10:13], v[154:157], v[194:197], v[10:13]
	v_mfma_f32_16x16x32_bf16 v[2:5], v[154:157], v[202:205], v[2:5]
	v_mfma_f32_16x16x32_bf16 v[10:13], v[158:161], v[198:201], v[10:13]
	v_mfma_f32_16x16x32_bf16 v[2:5], v[158:161], v[212:215], v[2:5]
	s_setprio 0
	s_barrier
	s_add_i32 s51, s51, 2
	s_add_u32 s40, s40, 0x100
	s_addc_u32 s49, s49, 0
	s_cmp_gt_u32 s51, 29
	s_mov_b64 s[4:5], s[6:7]
	s_cbranch_scc0 .LBB0_555
	s_ashr_i32 s4, s29, 31
	s_lshr_b32 s4, s4, 27
	s_add_i32 s4, s29, s4
	s_ashr_i32 s4, s4, 5
	v_lshl_or_b32 v148, s33, 8, v209
	s_mul_i32 s7, s4, 0xc000
	v_ashrrev_i32_e32 v149, 31, v148
	s_mul_hi_i32 s6, s4, 0xc000
	s_add_u32 s4, s22, s7
	s_addc_u32 s5, s23, s6
	v_lshlrev_b64 v[26:27], 2, v[148:149]
	v_lshl_add_u64 v[146:147], s[4:5], 0, v[26:27]
	s_add_u32 s4, s24, s7
	s_addc_u32 s5, s25, s6
	v_lshl_add_u64 v[160:161], s[4:5], 0, v[26:27]
	v_lshl_add_u64 v[178:179], s[46:47], 0, v[26:27]
	global_load_dwordx4 v[98:101], v[146:147], off offset:16
	global_load_dwordx4 v[102:105], v[146:147], off
	global_load_dwordx4 v[26:29], v[178:179], off offset:16
	global_load_dwordx4 v[30:33], v[178:179], off
	global_load_dwordx4 v[150:153], v[160:161], off offset:16
	global_load_dwordx4 v[154:157], v[160:161], off
	s_mov_b64 s[4:5], 0x40000
	s_waitcnt vmcnt(0)
	v_pk_mul_f32 v[188:189], v[140:141], v[100:101]
	v_pk_mul_f32 v[142:143], v[142:143], v[102:103]
	v_pk_mul_f32 v[144:145], v[144:145], v[104:105]
	v_pk_mul_f32 v[140:141], v[138:139], v[98:99]
	v_pk_mul_f32 v[136:137], v[136:137], v[104:105]
	v_pk_add_f32 v[156:157], v[156:157], 1.0 op_sel_hi:[1,0]
	v_pk_add_f32 v[154:155], v[154:155], 1.0 op_sel_hi:[1,0]
	v_pk_mul_f32 v[198:199], v[32:33], v[156:157]
	v_pk_mul_f32 v[200:201], v[30:31], v[154:155]
	v_pk_add_f32 v[30:31], v[152:153], 1.0 op_sel_hi:[1,0]
	v_pk_add_f32 v[32:33], v[150:151], 1.0 op_sel_hi:[1,0]
	v_pk_mul_f32 v[202:203], v[28:29], v[30:31]
	v_pk_mul_f32 v[204:205], v[26:27], v[32:33]
	global_load_dwordx4 v[26:29], v[146:147], off offset:528
	global_load_dwordx4 v[30:33], v[146:147], off offset:512
	global_load_dwordx4 v[156:159], v[178:179], off offset:528
	global_load_dwordx4 v[152:155], v[178:179], off offset:512
	s_nop 0
	global_load_dwordx4 v[178:181], v[160:161], off offset:528
	global_load_dwordx4 v[182:185], v[160:161], off offset:512
	v_pk_mul_f32 v[134:135], v[134:135], v[102:103]
	v_pk_mul_f32 v[130:131], v[130:131], v[98:99]
	v_pk_mul_f32 v[132:133], v[132:133], v[100:101]
	v_pk_mul_f32 v[128:129], v[128:129], v[104:105]
	v_pk_mul_f32 v[126:127], v[126:127], v[102:103]
	v_pk_mul_f32 v[122:123], v[122:123], v[98:99]
	v_pk_mul_f32 v[124:125], v[124:125], v[100:101]
	v_pk_mul_f32 v[120:121], v[120:121], v[104:105]
	v_pk_mul_f32 v[118:119], v[118:119], v[102:103]
	v_pk_mul_f32 v[114:115], v[114:115], v[98:99]
	v_pk_mul_f32 v[116:117], v[116:117], v[100:101]
	v_pk_mul_f32 v[112:113], v[112:113], v[104:105]
	v_pk_mul_f32 v[110:111], v[110:111], v[102:103]
	v_pk_mul_f32 v[106:107], v[106:107], v[98:99]
	v_pk_mul_f32 v[108:109], v[108:109], v[100:101]
	v_pk_mul_f32 v[96:97], v[96:97], v[104:105]
	v_pk_mul_f32 v[94:95], v[94:95], v[102:103]
	v_pk_mul_f32 v[90:91], v[90:91], v[98:99]
	v_pk_mul_f32 v[92:93], v[92:93], v[100:101]
	v_pk_mul_f32 v[88:89], v[88:89], v[104:105]
	v_pk_mul_f32 v[86:87], v[86:87], v[102:103]
	v_pk_mul_f32 v[82:83], v[82:83], v[98:99]
	v_pk_mul_f32 v[84:85], v[84:85], v[100:101]
	v_pk_mul_f32 v[80:81], v[80:81], v[104:105]
	v_pk_mul_f32 v[78:79], v[78:79], v[102:103]
	v_pk_mul_f32 v[74:75], v[74:75], v[98:99]
	v_pk_mul_f32 v[76:77], v[76:77], v[100:101]
	s_waitcnt vmcnt(5)
; __device__ __forceinline__ unsigned cvt_pk_bf16(float lo, float hi) { unsigned r; asm volatile("v_cvt_pk_bf16_f32 %0, %1, %2" : "=v"(r) : "v"(lo), "v"(hi)); return r; }
;     __device__ __forceinline__ void operator()(const f32x4 (&acc)[2][2][4][2], const Unit& u, int wr, int wc, int fr, int fq) const {
;     ...
;                 for (int m = 0; m < 4; ++m) { const size_t off = (size_t)(row0 + ai * HALF + m * 16) * 2048 + col0 + bj * HALF;
;                     f32x4 x0 = __builtin_nontemporal_load((const f32x4*)(base + off)), x1 = __builtin_nontemporal_load((const f32x4*)(base + off + 4));
;                     if constexpr (HAS_DIN) { const u32x4 dw = __builtin_nontemporal_load((const u32x4*)(dbuf + off));
;                         x0 += (f32x4){__builtin_bit_cast(float, dw.x << 16), __builtin_bit_cast(float, dw.x & 0xffff0000u), __builtin_bit_cast(float, dw.y << 16), __builtin_bit_cast(float, dw.y & 0xffff0000u)};
;                         x1 += (f32x4){__builtin_bit_cast(float, dw.z << 16), __builtin_bit_cast(float, dw.z & 0xffff0000u), __builtin_bit_cast(float, dw.w << 16), __builtin_bit_cast(float, dw.w & 0xffff0000u)}; }
;                     f32x4 o0, o1;
;                     if constexpr (OUT_DELTA) { const f32x4 d0 = g0 * acc[ai][bj][m][0], d1 = g1 * acc[ai][bj][m][1];
;                         u32x4 w; w.x = cvt_pk_bf16(d0[0], d0[1]); w.y = cvt_pk_bf16(d0[2], d0[3]); w.z = cvt_pk_bf16(d1[0], d1[1]); w.w = cvt_pk_bf16(d1[2], d1[3]);
;                         *(u32x4*)(dbuf + off) = w;
;                         o0 = x0 + (f32x4){__builtin_bit_cast(float, w.x << 16), __builtin_bit_cast(float, w.x & 0xffff0000u), __builtin_bit_cast(float, w.y << 16), __builtin_bit_cast(float, w.y & 0xffff0000u)};
;                         o1 = x1 + (f32x4){__builtin_bit_cast(float, w.z << 16), __builtin_bit_cast(float, w.z & 0xffff0000u), __builtin_bit_cast(float, w.w << 16), __builtin_bit_cast(float, w.w & 0xffff0000u)}; }
;                     else { o0 = x0 + g0 * acc[ai][bj][m][0]; o1 = x1 + g1 * acc[ai][bj][m][1]; *(f32x4*)(out + off) = o0; *(f32x4*)(out + off + 4) = o1; }
;                     if (Hn) { const f32x4 h0 = o0 * G0, h1 = o1 * G1;
;                         u32x4 w; w.x = cvt_pk_bf16(h0[0], h0[1]); w.y = cvt_pk_bf16(h0[2], h0[3]); w.z = cvt_pk_bf16(h1[0], h1[1]); w.w = cvt_pk_bf16(h1[2], h1[3]);
;                         *(u32x4*)(Hn + off) = w;
	v_pk_mul_f32 v[58:59], v[58:59], v[26:27]
	s_waitcnt vmcnt(4)
	v_pk_mul_f32 v[72:73], v[72:73], v[32:33]
	v_pk_mul_f32 v[70:71], v[70:71], v[30:31]
	v_pk_mul_f32 v[64:65], v[64:65], v[32:33]
	v_pk_mul_f32 v[62:63], v[62:63], v[30:31]
	s_waitcnt vmcnt(0)
	v_pk_add_f32 v[146:147], v[184:185], 1.0 op_sel_hi:[1,0]
	v_pk_add_f32 v[160:161], v[182:183], 1.0 op_sel_hi:[1,0]
	v_pk_mul_f32 v[150:151], v[154:155], v[146:147]
	v_pk_add_f32 v[146:147], v[180:181], 1.0 op_sel_hi:[1,0]
	v_pk_mul_f32 v[152:153], v[152:153], v[160:161]
	v_pk_mul_f32 v[154:155], v[158:159], v[146:147]
	v_lshl_add_u32 v146, s29, 8, v207
	v_ashrrev_i32_e32 v147, 31, v146
	v_lshlrev_b64 v[184:185], 11, v[146:147]
	v_lshl_add_u64 v[186:187], v[184:185], 0, v[148:149]
	v_pk_add_f32 v[160:161], v[178:179], 1.0 op_sel_hi:[1,0]
	v_lshl_add_u64 v[178:179], v[186:187], 2, s[44:45]
	v_pk_mul_f32 v[156:157], v[156:157], v[160:161]
	global_load_dwordx4 v[158:161], v[178:179], off nt
	global_load_dwordx4 v[180:183], v[178:179], off offset:16 nt
	v_cvt_pk_bf16_f32 v138, v142, v143
	v_lshlrev_b64 v[142:143], 1, v[186:187]
	v_cvt_pk_bf16_f32 v139, v144, v145
	v_cvt_pk_bf16_f32 v140, v140, v141
	v_cvt_pk_bf16_f32 v141, v188, v189
	v_lshl_add_u64 v[144:145], s[90:91], 0, v[142:143]
	global_store_dwordx4 v[144:145], v[138:141], off
	v_lshlrev_b32_e32 v144, 16, v140
	v_and_b32_e32 v145, 0xffff0000, v140
	v_lshlrev_b32_e32 v140, 16, v141
	v_and_b32_e32 v141, 0xffff0000, v141
	v_lshl_add_u64 v[142:143], s[96:97], 0, v[142:143]
	v_pk_mul_f32 v[60:61], v[60:61], v[28:29]
	v_pk_mul_f32 v[56:57], v[56:57], v[32:33]
	v_pk_mul_f32 v[54:55], v[54:55], v[30:31]
	v_pk_mul_f32 v[50:51], v[50:51], v[26:27]
	v_pk_mul_f32 v[52:53], v[52:53], v[28:29]
	v_pk_mul_f32 v[48:49], v[48:49], v[32:33]
	v_pk_mul_f32 v[46:47], v[46:47], v[30:31]
	v_pk_mul_f32 v[42:43], v[42:43], v[26:27]
	v_pk_mul_f32 v[44:45], v[44:45], v[28:29]
	v_pk_mul_f32 v[40:41], v[40:41], v[32:33]
	v_pk_mul_f32 v[38:39], v[38:39], v[30:31]
	v_pk_mul_f32 v[34:35], v[34:35], v[26:27]
	v_pk_mul_f32 v[36:37], v[36:37], v[28:29]
	v_pk_mul_f32 v[24:25], v[24:25], v[32:33]
	v_pk_mul_f32 v[22:23], v[22:23], v[30:31]
	v_pk_mul_f32 v[18:19], v[18:19], v[26:27]
	v_pk_mul_f32 v[20:21], v[20:21], v[28:29]
	v_pk_mul_f32 v[16:17], v[16:17], v[32:33]
	v_pk_mul_f32 v[14:15], v[14:15], v[30:31]
	v_pk_mul_f32 v[10:11], v[10:11], v[26:27]
	v_pk_mul_f32 v[12:13], v[12:13], v[28:29]
	v_pk_mul_f32 v[8:9], v[8:9], v[32:33]
	v_pk_mul_f32 v[6:7], v[6:7], v[30:31]
	v_pk_mul_f32 v[2:3], v[2:3], v[26:27]
	v_pk_mul_f32 v[4:5], v[4:5], v[28:29]
	s_waitcnt vmcnt(1)
	v_pk_add_f32 v[182:183], v[182:183], v[140:141]
	v_lshlrev_b32_e32 v140, 16, v138
	v_and_b32_e32 v141, 0xffff0000, v138
	v_lshlrev_b32_e32 v138, 16, v139
	v_and_b32_e32 v139, 0xffff0000, v139
	v_pk_add_f32 v[158:159], v[158:159], v[140:141]
	v_pk_add_f32 v[160:161], v[160:161], v[138:139]
	v_pk_mul_f32 v[138:139], v[200:201], v[158:159]
	v_pk_add_f32 v[144:145], v[180:181], v[144:145]
	v_pk_mul_f32 v[140:141], v[198:199], v[160:161]
	v_cvt_pk_bf16_f32 v138, v138, v139
	v_pk_mul_f32 v[180:181], v[202:203], v[182:183]
	v_cvt_pk_bf16_f32 v139, v140, v141
	v_pk_mul_f32 v[186:187], v[204:205], v[144:145]
	s_nop 0
	v_cvt_pk_bf16_f32 v140, v186, v187
	v_cvt_pk_bf16_f32 v141, v180, v181
	global_store_dwordx4 v[142:143], v[138:141], off
	s_nop 1
	v_mul_f32_e32 v138, v159, v159
	v_mul_f32_e32 v139, v161, v161
	v_fmac_f32_e32 v138, v158, v158
	v_fmac_f32_e32 v139, v160, v160
	v_add_f32_e32 v138, v138, v139
	v_mul_f32_e32 v139, v145, v145
	v_mul_f32_e32 v140, v183, v183
	v_fmac_f32_e32 v139, v144, v144
	v_fmac_f32_e32 v140, v182, v182
	v_add_f32_e32 v139, v139, v140
	v_add_f32_e32 v211, v138, v139
	v_or_b32_e32 v138, 16, v146
	v_ashrrev_i32_e32 v139, 31, v138
	v_lshlrev_b64 v[140:141], 11, v[138:139]
	v_lshl_add_u64 v[180:181], v[140:141], 0, v[148:149]
	v_lshl_add_u64 v[138:139], v[180:181], 2, s[44:45]
	global_load_dwordx4 v[142:145], v[138:139], off nt
	global_load_dwordx4 v[158:161], v[138:139], off offset:16 nt
	v_lshlrev_b64 v[180:181], 1, v[180:181]
	v_cvt_pk_bf16_f32 v134, v134, v135
	v_cvt_pk_bf16_f32 v135, v136, v137
	v_cvt_pk_bf16_f32 v136, v130, v131
	v_cvt_pk_bf16_f32 v137, v132, v133
	v_lshl_add_u64 v[130:131], s[90:91], 0, v[180:181]
	global_store_dwordx4 v[130:131], v[134:137], off
	v_lshlrev_b32_e32 v132, 16, v136
	v_and_b32_e32 v133, 0xffff0000, v136
	v_lshlrev_b32_e32 v130, 16, v137
	v_and_b32_e32 v131, 0xffff0000, v137
	v_lshlrev_b32_e32 v136, 16, v134
	v_and_b32_e32 v137, 0xffff0000, v134
	v_lshlrev_b32_e32 v134, 16, v135
	v_and_b32_e32 v135, 0xffff0000, v135
	s_waitcnt vmcnt(2)
	v_pk_add_f32 v[134:135], v[144:145], v[134:135]
	s_waitcnt vmcnt(1)
	v_pk_add_f32 v[130:131], v[160:161], v[130:131]
	v_pk_add_f32 v[136:137], v[142:143], v[136:137]
	v_pk_add_f32 v[132:133], v[158:159], v[132:133]
	v_pk_mul_f32 v[144:145], v[198:199], v[134:135]
	v_pk_mul_f32 v[142:143], v[200:201], v[136:137]
	v_pk_mul_f32 v[158:159], v[202:203], v[130:131]
	v_pk_mul_f32 v[160:161], v[204:205], v[132:133]
	v_cvt_pk_bf16_f32 v142, v142, v143
	v_cvt_pk_bf16_f32 v143, v144, v145
	s_nop 0
	v_cvt_pk_bf16_f32 v144, v160, v161
	v_cvt_pk_bf16_f32 v145, v158, v159
	v_lshl_add_u64 v[158:159], s[96:97], 0, v[180:181]
	global_store_dwordx4 v[158:159], v[142:145], off
	s_nop 1
	v_or_b32_e32 v142, 32, v146
	v_ashrrev_i32_e32 v143, 31, v142
	v_lshlrev_b64 v[144:145], 11, v[142:143]
	v_lshl_add_u64 v[186:187], v[144:145], 0, v[148:149]
	v_lshl_add_u64 v[142:143], v[186:187], 2, s[44:45]
	global_load_dwordx4 v[158:161], v[142:143], off nt
	global_load_dwordx4 v[180:183], v[142:143], off offset:16 nt
	v_lshlrev_b64 v[186:187], 1, v[186:187]
	v_cvt_pk_bf16_f32 v126, v126, v127
	v_cvt_pk_bf16_f32 v127, v128, v129
	v_cvt_pk_bf16_f32 v128, v122, v123
	v_cvt_pk_bf16_f32 v129, v124, v125
	v_lshl_add_u64 v[122:123], s[90:91], 0, v[186:187]
	global_store_dwordx4 v[122:123], v[126:129], off
	v_lshlrev_b32_e32 v124, 16, v128
	v_and_b32_e32 v125, 0xffff0000, v128
	v_lshlrev_b32_e32 v122, 16, v129
	v_and_b32_e32 v123, 0xffff0000, v129
	v_lshlrev_b32_e32 v128, 16, v126
	v_and_b32_e32 v129, 0xffff0000, v126
	v_lshlrev_b32_e32 v126, 16, v127
	v_and_b32_e32 v127, 0xffff0000, v127
	s_waitcnt vmcnt(2)
; __device__ __forceinline__ unsigned cvt_pk_bf16(float lo, float hi) { unsigned r; asm volatile("v_cvt_pk_bf16_f32 %0, %1, %2" : "=v"(r) : "v"(lo), "v"(hi)); return r; }
;     __device__ __forceinline__ void operator()(const f32x4 (&acc)[2][2][4][2], const Unit& u, int wr, int wc, int fr, int fq) const {
;     ...
;                 for (int m = 0; m < 4; ++m) { const size_t off = (size_t)(row0 + ai * HALF + m * 16) * 2048 + col0 + bj * HALF;
;                     f32x4 x0 = __builtin_nontemporal_load((const f32x4*)(base + off)), x1 = __builtin_nontemporal_load((const f32x4*)(base + off + 4));
;                     if constexpr (HAS_DIN) { const u32x4 dw = __builtin_nontemporal_load((const u32x4*)(dbuf + off));
;                         x0 += (f32x4){__builtin_bit_cast(float, dw.x << 16), __builtin_bit_cast(float, dw.x & 0xffff0000u), __builtin_bit_cast(float, dw.y << 16), __builtin_bit_cast(float, dw.y & 0xffff0000u)};
;                         x1 += (f32x4){__builtin_bit_cast(float, dw.z << 16), __builtin_bit_cast(float, dw.z & 0xffff0000u), __builtin_bit_cast(float, dw.w << 16), __builtin_bit_cast(float, dw.w & 0xffff0000u)}; }
;                     f32x4 o0, o1;
;                     if constexpr (OUT_DELTA) { const f32x4 d0 = g0 * acc[ai][bj][m][0], d1 = g1 * acc[ai][bj][m][1];
;                         u32x4 w; w.x = cvt_pk_bf16(d0[0], d0[1]); w.y = cvt_pk_bf16(d0[2], d0[3]); w.z = cvt_pk_bf16(d1[0], d1[1]); w.w = cvt_pk_bf16(d1[2], d1[3]);
;                         *(u32x4*)(dbuf + off) = w;
;                         o0 = x0 + (f32x4){__builtin_bit_cast(float, w.x << 16), __builtin_bit_cast(float, w.x & 0xffff0000u), __builtin_bit_cast(float, w.y << 16), __builtin_bit_cast(float, w.y & 0xffff0000u)};
;                         o1 = x1 + (f32x4){__builtin_bit_cast(float, w.z << 16), __builtin_bit_cast(float, w.z & 0xffff0000u), __builtin_bit_cast(float, w.w << 16), __builtin_bit_cast(float, w.w & 0xffff0000u)}; }
;                     else { o0 = x0 + g0 * acc[ai][bj][m][0]; o1 = x1 + g1 * acc[ai][bj][m][1]; *(f32x4*)(out + off) = o0; *(f32x4*)(out + off + 4) = o1; }
;                     if (Hn) { const f32x4 h0 = o0 * G0, h1 = o1 * G1;
;                         u32x4 w; w.x = cvt_pk_bf16(h0[0], h0[1]); w.y = cvt_pk_bf16(h0[2], h0[3]); w.z = cvt_pk_bf16(h1[0], h1[1]); w.w = cvt_pk_bf16(h1[2], h1[3]);
;                         *(u32x4*)(Hn + off) = w;
	v_pk_add_f32 v[126:127], v[160:161], v[126:127]
	s_waitcnt vmcnt(1)
	v_pk_add_f32 v[122:123], v[182:183], v[122:123]
	v_pk_add_f32 v[128:129], v[158:159], v[128:129]
	v_pk_add_f32 v[124:125], v[180:181], v[124:125]
	v_pk_mul_f32 v[160:161], v[198:199], v[126:127]
	v_pk_mul_f32 v[158:159], v[200:201], v[128:129]
	v_pk_mul_f32 v[180:181], v[202:203], v[122:123]
	v_pk_mul_f32 v[182:183], v[204:205], v[124:125]
	v_cvt_pk_bf16_f32 v158, v158, v159
	v_cvt_pk_bf16_f32 v159, v160, v161
	s_nop 0
	v_cvt_pk_bf16_f32 v160, v182, v183
	v_cvt_pk_bf16_f32 v161, v180, v181
	v_lshl_add_u64 v[180:181], s[96:97], 0, v[186:187]
	global_store_dwordx4 v[180:181], v[158:161], off
	s_nop 1
	v_or_b32_e32 v158, 48, v146
	v_ashrrev_i32_e32 v159, 31, v158
	v_lshlrev_b64 v[160:161], 11, v[158:159]
	v_lshl_add_u64 v[190:191], v[160:161], 0, v[148:149]
	v_lshl_add_u64 v[158:159], v[190:191], 2, s[44:45]
	global_load_dwordx4 v[180:183], v[158:159], off nt
	global_load_dwordx4 v[186:189], v[158:159], off offset:16 nt
	v_lshlrev_b64 v[190:191], 1, v[190:191]
	v_cvt_pk_bf16_f32 v118, v118, v119
	v_cvt_pk_bf16_f32 v119, v120, v121
	v_cvt_pk_bf16_f32 v120, v114, v115
	v_cvt_pk_bf16_f32 v121, v116, v117
	v_lshl_add_u64 v[114:115], s[90:91], 0, v[190:191]
	global_store_dwordx4 v[114:115], v[118:121], off
	v_lshlrev_b32_e32 v116, 16, v120
	v_and_b32_e32 v117, 0xffff0000, v120
	v_lshlrev_b32_e32 v114, 16, v121
	v_and_b32_e32 v115, 0xffff0000, v121
	v_lshlrev_b32_e32 v120, 16, v118
	v_and_b32_e32 v121, 0xffff0000, v118
	v_lshlrev_b32_e32 v118, 16, v119
	v_and_b32_e32 v119, 0xffff0000, v119
	s_waitcnt vmcnt(2)
	v_pk_add_f32 v[118:119], v[182:183], v[118:119]
	s_waitcnt vmcnt(1)
	v_pk_add_f32 v[114:115], v[188:189], v[114:115]
	v_pk_add_f32 v[120:121], v[180:181], v[120:121]
	v_pk_add_f32 v[116:117], v[186:187], v[116:117]
	v_pk_mul_f32 v[182:183], v[198:199], v[118:119]
	v_pk_mul_f32 v[180:181], v[200:201], v[120:121]
	v_pk_mul_f32 v[186:187], v[202:203], v[114:115]
	v_pk_mul_f32 v[188:189], v[204:205], v[116:117]
	v_cvt_pk_bf16_f32 v180, v180, v181
	v_cvt_pk_bf16_f32 v181, v182, v183
	s_nop 0
	v_cvt_pk_bf16_f32 v182, v188, v189
	v_cvt_pk_bf16_f32 v183, v186, v187
	v_lshl_add_u64 v[186:187], s[96:97], 0, v[190:191]
	global_store_dwordx4 v[186:187], v[180:183], off
	s_nop 1
	v_lshl_add_u64 v[182:183], v[184:185], 0, s[4:5]
	v_lshl_add_u64 v[194:195], v[182:183], 0, v[148:149]
	v_lshl_add_u64 v[180:181], v[194:195], 2, s[44:45]
	global_load_dwordx4 v[186:189], v[180:181], off nt
	global_load_dwordx4 v[190:193], v[180:181], off offset:16 nt
	v_lshlrev_b64 v[194:195], 1, v[194:195]
	v_cvt_pk_bf16_f32 v110, v110, v111
	v_cvt_pk_bf16_f32 v111, v112, v113
	v_cvt_pk_bf16_f32 v112, v106, v107
	v_cvt_pk_bf16_f32 v113, v108, v109
	v_lshl_add_u64 v[106:107], s[90:91], 0, v[194:195]
	global_store_dwordx4 v[106:107], v[110:113], off
	v_lshlrev_b32_e32 v108, 16, v112
	v_and_b32_e32 v109, 0xffff0000, v112
	v_lshlrev_b32_e32 v106, 16, v113
	v_and_b32_e32 v107, 0xffff0000, v113
	v_lshlrev_b32_e32 v112, 16, v110
	v_and_b32_e32 v113, 0xffff0000, v110
	v_lshlrev_b32_e32 v110, 16, v111
	v_and_b32_e32 v111, 0xffff0000, v111
	s_mov_b64 s[4:5], 0x48000
	s_waitcnt vmcnt(2)
	v_pk_add_f32 v[110:111], v[188:189], v[110:111]
	s_waitcnt vmcnt(1)
	v_pk_add_f32 v[106:107], v[192:193], v[106:107]
	v_pk_add_f32 v[112:113], v[186:187], v[112:113]
	v_pk_add_f32 v[108:109], v[190:191], v[108:109]
	v_pk_mul_f32 v[188:189], v[198:199], v[110:111]
	v_pk_mul_f32 v[186:187], v[200:201], v[112:113]
	v_pk_mul_f32 v[190:191], v[202:203], v[106:107]
	v_pk_mul_f32 v[192:193], v[204:205], v[108:109]
	v_cvt_pk_bf16_f32 v186, v186, v187
	v_cvt_pk_bf16_f32 v187, v188, v189
	s_nop 0
	v_cvt_pk_bf16_f32 v188, v192, v193
	v_cvt_pk_bf16_f32 v189, v190, v191
	v_lshl_add_u64 v[190:191], s[96:97], 0, v[194:195]
	global_store_dwordx4 v[190:191], v[186:189], off
	s_nop 1
	v_lshl_add_u64 v[188:189], v[184:185], 0, s[4:5]
	v_lshl_add_u64 v[212:213], v[188:189], 0, v[148:149]
	v_lshl_add_u64 v[186:187], v[212:213], 2, s[44:45]
	global_load_dwordx4 v[190:193], v[186:187], off nt
	global_load_dwordx4 v[194:197], v[186:187], off offset:16 nt
	v_lshlrev_b64 v[212:213], 1, v[212:213]
	v_cvt_pk_bf16_f32 v94, v94, v95
	v_cvt_pk_bf16_f32 v95, v96, v97
	v_cvt_pk_bf16_f32 v96, v90, v91
	v_cvt_pk_bf16_f32 v97, v92, v93
	v_lshl_add_u64 v[90:91], s[90:91], 0, v[212:213]
	global_store_dwordx4 v[90:91], v[94:97], off
	v_lshlrev_b32_e32 v92, 16, v96
	v_and_b32_e32 v93, 0xffff0000, v96
	v_lshlrev_b32_e32 v90, 16, v97
	v_and_b32_e32 v91, 0xffff0000, v97
	v_lshlrev_b32_e32 v96, 16, v94
	v_and_b32_e32 v97, 0xffff0000, v94
	v_lshlrev_b32_e32 v94, 16, v95
	v_and_b32_e32 v95, 0xffff0000, v95
	s_mov_b64 s[4:5], 0x50000
	s_waitcnt vmcnt(2)
	v_pk_add_f32 v[94:95], v[192:193], v[94:95]
	s_waitcnt vmcnt(1)
	v_pk_add_f32 v[90:91], v[196:197], v[90:91]
	v_pk_add_f32 v[96:97], v[190:191], v[96:97]
	v_pk_add_f32 v[92:93], v[194:195], v[92:93]
	v_pk_mul_f32 v[192:193], v[198:199], v[94:95]
	v_pk_mul_f32 v[190:191], v[200:201], v[96:97]
	v_pk_mul_f32 v[194:195], v[202:203], v[90:91]
	v_pk_mul_f32 v[196:197], v[204:205], v[92:93]
	v_cvt_pk_bf16_f32 v190, v190, v191
	v_cvt_pk_bf16_f32 v191, v192, v193
	s_nop 0
	v_cvt_pk_bf16_f32 v192, v196, v197
	v_cvt_pk_bf16_f32 v193, v194, v195
	v_lshl_add_u64 v[194:195], s[96:97], 0, v[212:213]
	global_store_dwordx4 v[194:195], v[190:193], off
	s_nop 1
	v_lshl_add_u64 v[192:193], v[184:185], 0, s[4:5]
	v_lshl_add_u64 v[220:221], v[192:193], 0, v[148:149]
	v_lshl_add_u64 v[190:191], v[220:221], 2, s[44:45]
	global_load_dwordx4 v[194:197], v[190:191], off nt
	global_load_dwordx4 v[212:215], v[190:191], off offset:16 nt
	v_lshlrev_b64 v[220:221], 1, v[220:221]
	v_cvt_pk_bf16_f32 v86, v86, v87
	v_cvt_pk_bf16_f32 v87, v88, v89
	v_cvt_pk_bf16_f32 v88, v82, v83
	v_cvt_pk_bf16_f32 v89, v84, v85
	v_lshl_add_u64 v[82:83], s[90:91], 0, v[220:221]
	global_store_dwordx4 v[82:83], v[86:89], off
	v_lshlrev_b32_e32 v84, 16, v88
	v_and_b32_e32 v85, 0xffff0000, v88
	v_lshlrev_b32_e32 v82, 16, v89
	v_and_b32_e32 v83, 0xffff0000, v89
	v_lshlrev_b32_e32 v88, 16, v86
	v_and_b32_e32 v89, 0xffff0000, v86
	v_lshlrev_b32_e32 v86, 16, v87
	v_and_b32_e32 v87, 0xffff0000, v87
	s_mov_b64 s[4:5], 0x58000
	s_waitcnt vmcnt(2)
; __device__ __forceinline__ unsigned cvt_pk_bf16(float lo, float hi) { unsigned r; asm volatile("v_cvt_pk_bf16_f32 %0, %1, %2" : "=v"(r) : "v"(lo), "v"(hi)); return r; }
;     __device__ __forceinline__ void operator()(const f32x4 (&acc)[2][2][4][2], const Unit& u, int wr, int wc, int fr, int fq) const {
;     ...
;                 for (int m = 0; m < 4; ++m) { const size_t off = (size_t)(row0 + ai * HALF + m * 16) * 2048 + col0 + bj * HALF;
;                     f32x4 x0 = __builtin_nontemporal_load((const f32x4*)(base + off)), x1 = __builtin_nontemporal_load((const f32x4*)(base + off + 4));
;                     if constexpr (HAS_DIN) { const u32x4 dw = __builtin_nontemporal_load((const u32x4*)(dbuf + off));
;                         x0 += (f32x4){__builtin_bit_cast(float, dw.x << 16), __builtin_bit_cast(float, dw.x & 0xffff0000u), __builtin_bit_cast(float, dw.y << 16), __builtin_bit_cast(float, dw.y & 0xffff0000u)};
;                         x1 += (f32x4){__builtin_bit_cast(float, dw.z << 16), __builtin_bit_cast(float, dw.z & 0xffff0000u), __builtin_bit_cast(float, dw.w << 16), __builtin_bit_cast(float, dw.w & 0xffff0000u)}; }
;                     f32x4 o0, o1;
;                     if constexpr (OUT_DELTA) { const f32x4 d0 = g0 * acc[ai][bj][m][0], d1 = g1 * acc[ai][bj][m][1];
;                         u32x4 w; w.x = cvt_pk_bf16(d0[0], d0[1]); w.y = cvt_pk_bf16(d0[2], d0[3]); w.z = cvt_pk_bf16(d1[0], d1[1]); w.w = cvt_pk_bf16(d1[2], d1[3]);
;                         *(u32x4*)(dbuf + off) = w;
;                         o0 = x0 + (f32x4){__builtin_bit_cast(float, w.x << 16), __builtin_bit_cast(float, w.x & 0xffff0000u), __builtin_bit_cast(float, w.y << 16), __builtin_bit_cast(float, w.y & 0xffff0000u)};
;                         o1 = x1 + (f32x4){__builtin_bit_cast(float, w.z << 16), __builtin_bit_cast(float, w.z & 0xffff0000u), __builtin_bit_cast(float, w.w << 16), __builtin_bit_cast(float, w.w & 0xffff0000u)}; }
;                     else { o0 = x0 + g0 * acc[ai][bj][m][0]; o1 = x1 + g1 * acc[ai][bj][m][1]; *(f32x4*)(out + off) = o0; *(f32x4*)(out + off + 4) = o1; }
;                     if (Hn) { const f32x4 h0 = o0 * G0, h1 = o1 * G1;
;                         u32x4 w; w.x = cvt_pk_bf16(h0[0], h0[1]); w.y = cvt_pk_bf16(h0[2], h0[3]); w.z = cvt_pk_bf16(h1[0], h1[1]); w.w = cvt_pk_bf16(h1[2], h1[3]);
;                         *(u32x4*)(Hn + off) = w;
	v_pk_add_f32 v[86:87], v[196:197], v[86:87]
	s_waitcnt vmcnt(1)
	v_pk_add_f32 v[82:83], v[214:215], v[82:83]
	v_pk_add_f32 v[88:89], v[194:195], v[88:89]
	v_pk_add_f32 v[84:85], v[212:213], v[84:85]
	v_pk_mul_f32 v[196:197], v[198:199], v[86:87]
	v_pk_mul_f32 v[194:195], v[200:201], v[88:89]
	v_pk_mul_f32 v[212:213], v[202:203], v[82:83]
	v_pk_mul_f32 v[214:215], v[204:205], v[84:85]
	v_cvt_pk_bf16_f32 v194, v194, v195
	v_cvt_pk_bf16_f32 v195, v196, v197
	s_nop 0
	v_cvt_pk_bf16_f32 v196, v214, v215
	v_cvt_pk_bf16_f32 v197, v212, v213
	v_lshl_add_u64 v[212:213], s[96:97], 0, v[220:221]
	global_store_dwordx4 v[212:213], v[194:197], off
	s_nop 1
	v_lshl_add_u64 v[196:197], v[184:185], 0, s[4:5]
	v_lshl_add_u64 v[224:225], v[196:197], 0, v[148:149]
	v_lshl_add_u64 v[194:195], v[224:225], 2, s[44:45]
	global_load_dwordx4 v[212:215], v[194:195], off nt
	global_load_dwordx4 v[220:223], v[194:195], off offset:16 nt
	v_lshlrev_b64 v[102:103], 1, v[224:225]
	v_cvt_pk_bf16_f32 v78, v78, v79
	v_cvt_pk_bf16_f32 v79, v80, v81
	v_cvt_pk_bf16_f32 v80, v74, v75
	v_cvt_pk_bf16_f32 v81, v76, v77
	v_lshl_add_u64 v[74:75], s[90:91], 0, v[102:103]
	global_store_dwordx4 v[74:75], v[78:81], off
	v_lshlrev_b32_e32 v76, 16, v80
	v_and_b32_e32 v77, 0xffff0000, v80
	v_lshlrev_b32_e32 v74, 16, v81
	v_and_b32_e32 v75, 0xffff0000, v81
	v_lshlrev_b32_e32 v80, 16, v78
	v_and_b32_e32 v81, 0xffff0000, v78
	v_lshlrev_b32_e32 v78, 16, v79
	v_and_b32_e32 v79, 0xffff0000, v79
	v_lshl_add_u64 v[102:103], s[96:97], 0, v[102:103]
	v_or_b32_e32 v148, 0x80, v148
	s_waitcnt vmcnt(2)
	v_pk_add_f32 v[78:79], v[214:215], v[78:79]
	v_pk_add_f32 v[80:81], v[212:213], v[80:81]
	s_waitcnt vmcnt(1)
	v_pk_add_f32 v[74:75], v[222:223], v[74:75]
	v_pk_add_f32 v[76:77], v[220:221], v[76:77]
	v_pk_mul_f32 v[100:101], v[198:199], v[78:79]
	v_pk_mul_f32 v[98:99], v[200:201], v[80:81]
	v_pk_mul_f32 v[104:105], v[202:203], v[74:75]
	v_pk_mul_f32 v[198:199], v[204:205], v[76:77]
	v_cvt_pk_bf16_f32 v98, v98, v99
	v_cvt_pk_bf16_f32 v99, v100, v101
	s_nop 0
	v_cvt_pk_bf16_f32 v100, v198, v199
	v_cvt_pk_bf16_f32 v101, v104, v105
	global_store_dwordx4 v[102:103], v[98:101], off
	global_load_dwordx4 v[100:103], v[178:179], off offset:512 nt
	global_load_dwordx4 v[198:201], v[178:179], off offset:528 nt
	v_lshl_add_u64 v[98:99], v[184:185], 0, v[148:149]
	v_pk_mul_f32 v[104:105], v[68:69], v[28:29]
	v_pk_mul_f32 v[68:69], v[66:67], v[26:27]
	v_cvt_pk_bf16_f32 v66, v70, v71
	v_cvt_pk_bf16_f32 v67, v72, v73
	s_nop 0
	v_cvt_pk_bf16_f32 v68, v68, v69
	v_cvt_pk_bf16_f32 v69, v104, v105
	v_lshlrev_b64 v[104:105], 1, v[98:99]
	v_lshl_add_u64 v[70:71], s[90:91], 0, v[104:105]
	global_store_dwordx4 v[70:71], v[66:69], off
	v_lshlrev_b32_e32 v72, 16, v68
	v_and_b32_e32 v73, 0xffff0000, v68
	v_lshlrev_b32_e32 v68, 16, v69
	v_and_b32_e32 v69, 0xffff0000, v69
	s_waitcnt vmcnt(1)
	v_pk_add_f32 v[70:71], v[200:201], v[68:69]
	v_lshlrev_b32_e32 v68, 16, v66
	v_and_b32_e32 v69, 0xffff0000, v66
	v_lshlrev_b32_e32 v66, 16, v67
	v_and_b32_e32 v67, 0xffff0000, v67
	v_pk_add_f32 v[98:99], v[102:103], v[66:67]
	v_pk_add_f32 v[100:101], v[100:101], v[68:69]
	v_pk_add_f32 v[72:73], v[198:199], v[72:73]
	v_pk_mul_f32 v[68:69], v[150:151], v[98:99]
	v_pk_mul_f32 v[66:67], v[152:153], v[100:101]
	v_pk_mul_f32 v[102:103], v[154:155], v[70:71]
	v_pk_mul_f32 v[178:179], v[156:157], v[72:73]
	v_cvt_pk_bf16_f32 v66, v66, v67
	v_cvt_pk_bf16_f32 v67, v68, v69
	s_nop 0
	v_cvt_pk_bf16_f32 v68, v178, v179
	v_cvt_pk_bf16_f32 v69, v102, v103
	v_lshl_add_u64 v[102:103], s[96:97], 0, v[104:105]
	global_store_dwordx4 v[102:103], v[66:69], off
	s_nop 1
	v_mul_f32_e32 v66, v101, v101
	v_mul_f32_e32 v67, v99, v99
	v_fmac_f32_e32 v66, v100, v100
	v_fmac_f32_e32 v67, v98, v98
	v_add_f32_e32 v66, v66, v67
	v_mul_f32_e32 v67, v73, v73
	v_mul_f32_e32 v68, v71, v71
	v_fmac_f32_e32 v67, v72, v72
	v_fmac_f32_e32 v68, v70, v70
	v_add_f32_e32 v67, v67, v68
	global_load_dwordx4 v[68:71], v[138:139], off offset:512 nt
	global_load_dwordx4 v[98:101], v[138:139], off offset:528 nt
	v_lshl_add_u64 v[72:73], v[140:141], 0, v[148:149]
	v_lshlrev_b64 v[72:73], 1, v[72:73]
	v_cvt_pk_bf16_f32 v62, v62, v63
	v_cvt_pk_bf16_f32 v63, v64, v65
	v_cvt_pk_bf16_f32 v64, v58, v59
	v_cvt_pk_bf16_f32 v65, v60, v61
	v_lshl_add_u64 v[58:59], s[90:91], 0, v[72:73]
	global_store_dwordx4 v[58:59], v[62:65], off
	v_lshlrev_b32_e32 v60, 16, v64
	v_and_b32_e32 v61, 0xffff0000, v64
	v_lshlrev_b32_e32 v58, 16, v65
	v_and_b32_e32 v59, 0xffff0000, v65
	v_lshlrev_b32_e32 v64, 16, v62
	v_and_b32_e32 v65, 0xffff0000, v62
	v_lshlrev_b32_e32 v62, 16, v63
	v_and_b32_e32 v63, 0xffff0000, v63
	v_lshl_add_u64 v[72:73], s[96:97], 0, v[72:73]
	v_add_f32_e32 v66, v66, v67
	v_add_f32_e32 v66, v211, v66
	s_waitcnt vmcnt(2)
	v_pk_add_f32 v[62:63], v[70:71], v[62:63]
	v_pk_add_f32 v[64:65], v[68:69], v[64:65]
	s_waitcnt vmcnt(1)
	v_pk_add_f32 v[58:59], v[100:101], v[58:59]
	v_pk_add_f32 v[60:61], v[98:99], v[60:61]
	v_pk_mul_f32 v[70:71], v[150:151], v[62:63]
	v_pk_mul_f32 v[68:69], v[152:153], v[64:65]
	v_pk_mul_f32 v[98:99], v[154:155], v[58:59]
	v_pk_mul_f32 v[100:101], v[156:157], v[60:61]
	v_cvt_pk_bf16_f32 v68, v68, v69
	v_cvt_pk_bf16_f32 v69, v70, v71
	s_nop 0
	v_cvt_pk_bf16_f32 v70, v100, v101
	v_cvt_pk_bf16_f32 v71, v98, v99
	global_store_dwordx4 v[72:73], v[68:71], off
	global_load_dwordx4 v[68:71], v[142:143], off offset:512 nt
	s_nop 0
	global_load_dwordx4 v[98:101], v[142:143], off offset:528 nt
	v_lshl_add_u64 v[72:73], v[144:145], 0, v[148:149]
	v_lshlrev_b64 v[72:73], 1, v[72:73]
	v_cvt_pk_bf16_f32 v54, v54, v55
	v_cvt_pk_bf16_f32 v55, v56, v57
	v_cvt_pk_bf16_f32 v56, v50, v51
	v_cvt_pk_bf16_f32 v57, v52, v53
	v_lshl_add_u64 v[50:51], s[90:91], 0, v[72:73]
	global_store_dwordx4 v[50:51], v[54:57], off
	v_lshlrev_b32_e32 v52, 16, v56
	v_and_b32_e32 v53, 0xffff0000, v56
	v_lshlrev_b32_e32 v50, 16, v57
	v_and_b32_e32 v51, 0xffff0000, v57
	v_lshlrev_b32_e32 v56, 16, v54
	v_and_b32_e32 v57, 0xffff0000, v54
	v_lshlrev_b32_e32 v54, 16, v55
	v_and_b32_e32 v55, 0xffff0000, v55
	v_lshl_add_u64 v[72:73], s[96:97], 0, v[72:73]
	s_waitcnt vmcnt(2)
; __device__ __forceinline__ unsigned cvt_pk_bf16(float lo, float hi) { unsigned r; asm volatile("v_cvt_pk_bf16_f32 %0, %1, %2" : "=v"(r) : "v"(lo), "v"(hi)); return r; }
;     __device__ __forceinline__ void operator()(const f32x4 (&acc)[2][2][4][2], const Unit& u, int wr, int wc, int fr, int fq) const {
;     ...
;                 for (int m = 0; m < 4; ++m) { const size_t off = (size_t)(row0 + ai * HALF + m * 16) * 2048 + col0 + bj * HALF;
;                     f32x4 x0 = __builtin_nontemporal_load((const f32x4*)(base + off)), x1 = __builtin_nontemporal_load((const f32x4*)(base + off + 4));
;                     if constexpr (HAS_DIN) { const u32x4 dw = __builtin_nontemporal_load((const u32x4*)(dbuf + off));
;                         x0 += (f32x4){__builtin_bit_cast(float, dw.x << 16), __builtin_bit_cast(float, dw.x & 0xffff0000u), __builtin_bit_cast(float, dw.y << 16), __builtin_bit_cast(float, dw.y & 0xffff0000u)};
;                         x1 += (f32x4){__builtin_bit_cast(float, dw.z << 16), __builtin_bit_cast(float, dw.z & 0xffff0000u), __builtin_bit_cast(float, dw.w << 16), __builtin_bit_cast(float, dw.w & 0xffff0000u)}; }
;                     f32x4 o0, o1;
;                     if constexpr (OUT_DELTA) { const f32x4 d0 = g0 * acc[ai][bj][m][0], d1 = g1 * acc[ai][bj][m][1];
;                         u32x4 w; w.x = cvt_pk_bf16(d0[0], d0[1]); w.y = cvt_pk_bf16(d0[2], d0[3]); w.z = cvt_pk_bf16(d1[0], d1[1]); w.w = cvt_pk_bf16(d1[2], d1[3]);
;                         *(u32x4*)(dbuf + off) = w;
;                         o0 = x0 + (f32x4){__builtin_bit_cast(float, w.x << 16), __builtin_bit_cast(float, w.x & 0xffff0000u), __builtin_bit_cast(float, w.y << 16), __builtin_bit_cast(float, w.y & 0xffff0000u)};
;                         o1 = x1 + (f32x4){__builtin_bit_cast(float, w.z << 16), __builtin_bit_cast(float, w.z & 0xffff0000u), __builtin_bit_cast(float, w.w << 16), __builtin_bit_cast(float, w.w & 0xffff0000u)}; }
;                     else { o0 = x0 + g0 * acc[ai][bj][m][0]; o1 = x1 + g1 * acc[ai][bj][m][1]; *(f32x4*)(out + off) = o0; *(f32x4*)(out + off + 4) = o1; }
;                     if (Hn) { const f32x4 h0 = o0 * G0, h1 = o1 * G1;
;                         u32x4 w; w.x = cvt_pk_bf16(h0[0], h0[1]); w.y = cvt_pk_bf16(h0[2], h0[3]); w.z = cvt_pk_bf16(h1[0], h1[1]); w.w = cvt_pk_bf16(h1[2], h1[3]);
;                         *(u32x4*)(Hn + off) = w;
	v_pk_add_f32 v[54:55], v[70:71], v[54:55]
	v_pk_add_f32 v[56:57], v[68:69], v[56:57]
	s_waitcnt vmcnt(1)
	v_pk_add_f32 v[50:51], v[100:101], v[50:51]
	v_pk_add_f32 v[52:53], v[98:99], v[52:53]
	v_pk_mul_f32 v[70:71], v[150:151], v[54:55]
	v_pk_mul_f32 v[68:69], v[152:153], v[56:57]
	v_pk_mul_f32 v[98:99], v[154:155], v[50:51]
	v_pk_mul_f32 v[100:101], v[156:157], v[52:53]
	v_cvt_pk_bf16_f32 v68, v68, v69
	v_cvt_pk_bf16_f32 v69, v70, v71
	s_nop 0
	v_cvt_pk_bf16_f32 v70, v100, v101
	v_cvt_pk_bf16_f32 v71, v98, v99
	global_store_dwordx4 v[72:73], v[68:71], off
	global_load_dwordx4 v[68:71], v[158:159], off offset:512 nt
	s_nop 0
	global_load_dwordx4 v[98:101], v[158:159], off offset:528 nt
	v_lshl_add_u64 v[72:73], v[160:161], 0, v[148:149]
	v_lshlrev_b64 v[72:73], 1, v[72:73]
	v_cvt_pk_bf16_f32 v46, v46, v47
	v_cvt_pk_bf16_f32 v47, v48, v49
	v_cvt_pk_bf16_f32 v48, v42, v43
	v_cvt_pk_bf16_f32 v49, v44, v45
	v_lshl_add_u64 v[42:43], s[90:91], 0, v[72:73]
	global_store_dwordx4 v[42:43], v[46:49], off
	v_lshlrev_b32_e32 v44, 16, v48
	v_and_b32_e32 v45, 0xffff0000, v48
	v_lshlrev_b32_e32 v42, 16, v49
	v_and_b32_e32 v43, 0xffff0000, v49
	v_lshlrev_b32_e32 v48, 16, v46
	v_and_b32_e32 v49, 0xffff0000, v46
	v_lshlrev_b32_e32 v46, 16, v47
	v_and_b32_e32 v47, 0xffff0000, v47
	v_lshl_add_u64 v[72:73], s[96:97], 0, v[72:73]
	s_waitcnt vmcnt(2)
	v_pk_add_f32 v[46:47], v[70:71], v[46:47]
	v_pk_add_f32 v[48:49], v[68:69], v[48:49]
	s_waitcnt vmcnt(1)
	v_pk_add_f32 v[42:43], v[100:101], v[42:43]
	v_pk_add_f32 v[44:45], v[98:99], v[44:45]
	v_pk_mul_f32 v[70:71], v[150:151], v[46:47]
	v_pk_mul_f32 v[68:69], v[152:153], v[48:49]
	v_pk_mul_f32 v[98:99], v[154:155], v[42:43]
	v_pk_mul_f32 v[100:101], v[156:157], v[44:45]
	v_cvt_pk_bf16_f32 v68, v68, v69
	v_cvt_pk_bf16_f32 v69, v70, v71
	s_nop 0
	v_cvt_pk_bf16_f32 v70, v100, v101
	v_cvt_pk_bf16_f32 v71, v98, v99
	global_store_dwordx4 v[72:73], v[68:71], off
	global_load_dwordx4 v[68:71], v[180:181], off offset:512 nt
	s_nop 0
	global_load_dwordx4 v[98:101], v[180:181], off offset:528 nt
	v_lshl_add_u64 v[72:73], v[182:183], 0, v[148:149]
	v_lshlrev_b64 v[72:73], 1, v[72:73]
	v_cvt_pk_bf16_f32 v38, v38, v39
	v_cvt_pk_bf16_f32 v39, v40, v41
	v_cvt_pk_bf16_f32 v40, v34, v35
	v_cvt_pk_bf16_f32 v41, v36, v37
	v_lshl_add_u64 v[34:35], s[90:91], 0, v[72:73]
	global_store_dwordx4 v[34:35], v[38:41], off
	v_lshlrev_b32_e32 v36, 16, v40
	v_and_b32_e32 v37, 0xffff0000, v40
	v_lshlrev_b32_e32 v34, 16, v41
	v_and_b32_e32 v35, 0xffff0000, v41
	v_lshlrev_b32_e32 v40, 16, v38
	v_and_b32_e32 v41, 0xffff0000, v38
	v_lshlrev_b32_e32 v38, 16, v39
	v_and_b32_e32 v39, 0xffff0000, v39
	v_lshl_add_u64 v[72:73], s[96:97], 0, v[72:73]
	s_waitcnt vmcnt(2)
	v_pk_add_f32 v[38:39], v[70:71], v[38:39]
	v_pk_add_f32 v[40:41], v[68:69], v[40:41]
	s_waitcnt vmcnt(1)
	v_pk_add_f32 v[34:35], v[100:101], v[34:35]
	v_pk_add_f32 v[36:37], v[98:99], v[36:37]
	v_pk_mul_f32 v[70:71], v[150:151], v[38:39]
	v_pk_mul_f32 v[68:69], v[152:153], v[40:41]
	v_pk_mul_f32 v[98:99], v[154:155], v[34:35]
	v_pk_mul_f32 v[100:101], v[156:157], v[36:37]
	v_cvt_pk_bf16_f32 v68, v68, v69
	v_cvt_pk_bf16_f32 v69, v70, v71
	s_nop 0
	v_cvt_pk_bf16_f32 v70, v100, v101
	v_cvt_pk_bf16_f32 v71, v98, v99
	global_store_dwordx4 v[72:73], v[68:71], off
	global_load_dwordx4 v[68:71], v[186:187], off offset:512 nt
	s_nop 0
	global_load_dwordx4 v[98:101], v[186:187], off offset:528 nt
	v_lshl_add_u64 v[72:73], v[188:189], 0, v[148:149]
	v_lshlrev_b64 v[72:73], 1, v[72:73]
	v_cvt_pk_bf16_f32 v22, v22, v23
	v_cvt_pk_bf16_f32 v23, v24, v25
	v_cvt_pk_bf16_f32 v24, v18, v19
	v_cvt_pk_bf16_f32 v25, v20, v21
	v_lshl_add_u64 v[18:19], s[90:91], 0, v[72:73]
	global_store_dwordx4 v[18:19], v[22:25], off
	v_lshlrev_b32_e32 v20, 16, v24
	v_and_b32_e32 v21, 0xffff0000, v24
	v_lshlrev_b32_e32 v18, 16, v25
	v_and_b32_e32 v19, 0xffff0000, v25
	v_lshlrev_b32_e32 v24, 16, v22
	v_and_b32_e32 v25, 0xffff0000, v22
	v_lshlrev_b32_e32 v22, 16, v23
	v_and_b32_e32 v23, 0xffff0000, v23
	v_lshl_add_u64 v[72:73], s[96:97], 0, v[72:73]
	s_waitcnt vmcnt(2)
	v_pk_add_f32 v[22:23], v[70:71], v[22:23]
	v_pk_add_f32 v[24:25], v[68:69], v[24:25]
	s_waitcnt vmcnt(1)
; __device__ __forceinline__ unsigned cvt_pk_bf16(float lo, float hi) { unsigned r; asm volatile("v_cvt_pk_bf16_f32 %0, %1, %2" : "=v"(r) : "v"(lo), "v"(hi)); return r; }
;     __device__ __forceinline__ void operator()(const f32x4 (&acc)[2][2][4][2], const Unit& u, int wr, int wc, int fr, int fq) const {
;     ...
;                 for (int m = 0; m < 4; ++m) { const size_t off = (size_t)(row0 + ai * HALF + m * 16) * 2048 + col0 + bj * HALF;
;                     f32x4 x0 = __builtin_nontemporal_load((const f32x4*)(base + off)), x1 = __builtin_nontemporal_load((const f32x4*)(base + off + 4));
;                     if constexpr (HAS_DIN) { const u32x4 dw = __builtin_nontemporal_load((const u32x4*)(dbuf + off));
;                         x0 += (f32x4){__builtin_bit_cast(float, dw.x << 16), __builtin_bit_cast(float, dw.x & 0xffff0000u), __builtin_bit_cast(float, dw.y << 16), __builtin_bit_cast(float, dw.y & 0xffff0000u)};
;                         x1 += (f32x4){__builtin_bit_cast(float, dw.z << 16), __builtin_bit_cast(float, dw.z & 0xffff0000u), __builtin_bit_cast(float, dw.w << 16), __builtin_bit_cast(float, dw.w & 0xffff0000u)}; }
;                     f32x4 o0, o1;
;                     if constexpr (OUT_DELTA) { const f32x4 d0 = g0 * acc[ai][bj][m][0], d1 = g1 * acc[ai][bj][m][1];
;                         u32x4 w; w.x = cvt_pk_bf16(d0[0], d0[1]); w.y = cvt_pk_bf16(d0[2], d0[3]); w.z = cvt_pk_bf16(d1[0], d1[1]); w.w = cvt_pk_bf16(d1[2], d1[3]);
;                         *(u32x4*)(dbuf + off) = w;
;                         o0 = x0 + (f32x4){__builtin_bit_cast(float, w.x << 16), __builtin_bit_cast(float, w.x & 0xffff0000u), __builtin_bit_cast(float, w.y << 16), __builtin_bit_cast(float, w.y & 0xffff0000u)};
;                         o1 = x1 + (f32x4){__builtin_bit_cast(float, w.z << 16), __builtin_bit_cast(float, w.z & 0xffff0000u), __builtin_bit_cast(float, w.w << 16), __builtin_bit_cast(float, w.w & 0xffff0000u)}; }
;                     else { o0 = x0 + g0 * acc[ai][bj][m][0]; o1 = x1 + g1 * acc[ai][bj][m][1]; *(f32x4*)(out + off) = o0; *(f32x4*)(out + off + 4) = o1; }
;                     if (Hn) { const f32x4 h0 = o0 * G0, h1 = o1 * G1;
;                         u32x4 w; w.x = cvt_pk_bf16(h0[0], h0[1]); w.y = cvt_pk_bf16(h0[2], h0[3]); w.z = cvt_pk_bf16(h1[0], h1[1]); w.w = cvt_pk_bf16(h1[2], h1[3]);
;                         *(u32x4*)(Hn + off) = w;
	v_pk_add_f32 v[18:19], v[100:101], v[18:19]
	v_pk_add_f32 v[20:21], v[98:99], v[20:21]
	v_pk_mul_f32 v[70:71], v[150:151], v[22:23]
	v_pk_mul_f32 v[68:69], v[152:153], v[24:25]
	v_pk_mul_f32 v[98:99], v[154:155], v[18:19]
	v_pk_mul_f32 v[100:101], v[156:157], v[20:21]
	v_cvt_pk_bf16_f32 v68, v68, v69
	v_cvt_pk_bf16_f32 v69, v70, v71
	s_nop 0
	v_cvt_pk_bf16_f32 v70, v100, v101
	v_cvt_pk_bf16_f32 v71, v98, v99
	global_store_dwordx4 v[72:73], v[68:71], off
	global_load_dwordx4 v[68:71], v[190:191], off offset:512 nt
	s_nop 0
	global_load_dwordx4 v[98:101], v[190:191], off offset:528 nt
	v_lshl_add_u64 v[72:73], v[192:193], 0, v[148:149]
	v_lshlrev_b64 v[72:73], 1, v[72:73]
	v_cvt_pk_bf16_f32 v14, v14, v15
	v_cvt_pk_bf16_f32 v15, v16, v17
	v_cvt_pk_bf16_f32 v16, v10, v11
	v_cvt_pk_bf16_f32 v17, v12, v13
	v_lshl_add_u64 v[10:11], s[90:91], 0, v[72:73]
	global_store_dwordx4 v[10:11], v[14:17], off
	v_lshlrev_b32_e32 v12, 16, v16
	v_and_b32_e32 v13, 0xffff0000, v16
	v_lshlrev_b32_e32 v10, 16, v17
	v_and_b32_e32 v11, 0xffff0000, v17
	v_lshlrev_b32_e32 v16, 16, v14
	v_and_b32_e32 v17, 0xffff0000, v14
	v_lshlrev_b32_e32 v14, 16, v15
	v_and_b32_e32 v15, 0xffff0000, v15
	v_lshl_add_u64 v[72:73], s[96:97], 0, v[72:73]
	s_waitcnt vmcnt(2)
	v_pk_add_f32 v[14:15], v[70:71], v[14:15]
	v_pk_add_f32 v[16:17], v[68:69], v[16:17]
	s_waitcnt vmcnt(1)
	v_pk_add_f32 v[10:11], v[100:101], v[10:11]
	v_pk_add_f32 v[12:13], v[98:99], v[12:13]
	v_pk_mul_f32 v[70:71], v[150:151], v[14:15]
	v_pk_mul_f32 v[68:69], v[152:153], v[16:17]
	v_pk_mul_f32 v[98:99], v[154:155], v[10:11]
	v_pk_mul_f32 v[100:101], v[156:157], v[12:13]
	v_cvt_pk_bf16_f32 v68, v68, v69
	v_cvt_pk_bf16_f32 v69, v70, v71
	s_nop 0
	v_cvt_pk_bf16_f32 v70, v100, v101
	v_cvt_pk_bf16_f32 v71, v98, v99
	global_store_dwordx4 v[72:73], v[68:71], off
	global_load_dwordx4 v[68:71], v[194:195], off offset:512 nt
	s_nop 0
	global_load_dwordx4 v[98:101], v[194:195], off offset:528 nt
	v_lshl_add_u64 v[72:73], v[196:197], 0, v[148:149]
	v_lshlrev_b64 v[30:31], 1, v[72:73]
	v_cvt_pk_bf16_f32 v6, v6, v7
	v_cvt_pk_bf16_f32 v7, v8, v9
	v_cvt_pk_bf16_f32 v8, v2, v3
	v_cvt_pk_bf16_f32 v9, v4, v5
	v_lshl_add_u64 v[2:3], s[90:91], 0, v[30:31]
	global_store_dwordx4 v[2:3], v[6:9], off
	v_lshlrev_b32_e32 v4, 16, v8
	v_and_b32_e32 v5, 0xffff0000, v8
	v_lshlrev_b32_e32 v2, 16, v9
	v_and_b32_e32 v3, 0xffff0000, v9
	v_lshlrev_b32_e32 v8, 16, v6
	v_and_b32_e32 v9, 0xffff0000, v6
	v_lshlrev_b32_e32 v6, 16, v7
	v_and_b32_e32 v7, 0xffff0000, v7
	v_lshl_add_u64 v[30:31], s[96:97], 0, v[30:31]
	s_waitcnt vmcnt(2)
	v_pk_add_f32 v[8:9], v[68:69], v[8:9]
	v_pk_add_f32 v[6:7], v[70:71], v[6:7]
	v_pk_mul_f32 v[26:27], v[152:153], v[8:9]
	s_waitcnt vmcnt(1)
	v_pk_add_f32 v[2:3], v[100:101], v[2:3]
	v_pk_add_f32 v[4:5], v[98:99], v[4:5]
	v_pk_mul_f32 v[28:29], v[150:151], v[6:7]
	v_cvt_pk_bf16_f32 v26, v26, v27
	v_pk_mul_f32 v[32:33], v[154:155], v[2:3]
	v_cvt_pk_bf16_f32 v27, v28, v29
	v_pk_mul_f32 v[68:69], v[156:157], v[4:5]
	s_nop 0
	v_cvt_pk_bf16_f32 v28, v68, v69
	v_cvt_pk_bf16_f32 v29, v32, v33
	global_store_dwordx4 v[30:31], v[26:29], off
	s_nop 1
	v_and_b32_e32 v27, 64, v218
	v_xor_b32_e32 v26, 16, v218
	v_add_u32_e32 v27, 64, v27
	v_cmp_lt_i32_e32 vcc, v26, v27
	s_nop 1
	v_cndmask_b32_e32 v26, v218, v26, vcc
	v_lshlrev_b32_e32 v28, 2, v26
	v_xor_b32_e32 v26, 32, v218
	v_cmp_lt_i32_e32 vcc, v26, v27
	s_nop 1
	v_cndmask_b32_e32 v26, v218, v26, vcc
	v_lshlrev_b32_e32 v29, 2, v26
	ds_bpermute_b32 v26, v28, v66
	s_waitcnt lgkmcnt(0)
	v_add_f32_e32 v30, v66, v26
	ds_bpermute_b32 v31, v29, v30
	v_lshl_add_u64 v[26:27], v[146:147], 3, s[42:43]
	s_and_saveexec_b64 s[4:5], s[0:1]
	s_mov_b32 s8, 0x2f800000
	s_mov_b32 s9, 0xcf800000
	s_cbranch_execz .LBB0_558
	s_waitcnt lgkmcnt(0)
	v_add_f32_e32 v30, v30, v31
	v_mul_f32_e32 v30, 0x47800000, v30
	v_rndne_f32_e32 v30, v30
	v_mul_f32_e64 v31, |v30|, s8
	v_floor_f32_e32 v31, v31
	v_fma_f32 v32, v31, s9, |v30|
	v_cvt_u32_f32_e32 v32, v32
	v_cvt_u32_f32_e32 v31, v31
	v_ashrrev_i32_e32 v33, 31, v30
	v_xor_b32_e32 v30, v32, v33
	v_xor_b32_e32 v31, v31, v33
	v_sub_co_u32_e32 v30, vcc, v30, v33
	s_nop 1
	v_subb_co_u32_e32 v31, vcc, v31, v33, vcc
	global_atomic_add_x2 v[26:27], v[30:31], off

; #define PG8_STAGE(bufoff, gbase, voff) do { const char* gb_ = (const char*)(gbase); asm volatile("" : "+s"(gb_)); _Pragma("unroll") for (int _i = 0; _i < 2; ++_i) { unsigned vo_ = (voff)[_i]; asm volatile("" : "+v"(vo_));        \
;         __builtin_amdgcn_global_load_lds((const unsigned*)(gb_ + vo_), (PG8_LAS unsigned*)(lds + (bufoff) + ldsw + _i * 8192), 16, 0, 0); } } while (0)
; #define PG8_LDA(dst, b, h) do { _Pragma("unroll") for (int m = 0; m < 4; ++m) _Pragma("unroll") for (int k = 0; k < 2; ++k) dst[m][k] = *(const PG8_LAS bf16x8*)(lds + PG8_SA(b, h) + aoff + m * 2048 + k * 1024); } while (0)
; #define PG8_LDB(dst, b, h) do { _Pragma("unroll") for (int n = 0; n < 2; ++n) _Pragma("unroll") for (int k = 0; k < 2; ++k) dst[n][k] = *(const PG8_LAS bf16x8*)(lds + PG8_SB(b, h) + boff + n * 2048 + k * 1024); } while (0)
; #define PG8_MMA(ai, bj, At, Bt) do { __builtin_amdgcn_s_setprio(1); _Pragma("unroll") for (int m = 0; m < 4; ++m) _Pragma("unroll") for (int n = 0; n < 2; ++n) _Pragma("unroll") for (int k = 0; k < 2; ++k) \
;         acc[ai][bj][m][n] = __builtin_amdgcn_mfma_f32_16x16x32_bf16(Bt[n][k], At[m][k], acc[ai][bj][m][n], 0, 0, 0); __builtin_amdgcn_s_setprio(0); } while (0)
; #define PG8_WAIT_V(n) asm volatile("s_waitcnt vmcnt(" #n ")" ::: "memory")
; #define PG8_WAIT_L(n) asm volatile("s_waitcnt lgkmcnt(" #n ")" ::: "memory")
; template <class Epi, class Sched, bool ALIGN_EPI = false, bool SP2 = false>
; __device__ __forceinline__ void gemm_phase(PG8_LAS unsigned char* lds, const Gemm g, const Sched& S, const Epi& E) {
;     ...
;             const bool last = (t == nt - 2);
;             const char* a1 = cA + (size_t)(t + 1) * kstep;
;             const char* a2 = last ? nA : cA + (size_t)(t + 2) * kstep; const char* b2 = last ? nB : cB + (size_t)(t + 2) * kstep;
;             const char* a3 = a2 + kstep; const char* b3 = b2 + kstep;
;             if (last && has_next) S.a_ready(nxt);
;             if constexpr (SP2) {
;             PG8_LDB(B0, 0, 0); PG8_LDB(B1, 0, 1); PG8_SCHED; PG8_LDA(At, 0, 0); PG8_STAGE(PG8_SA(1, 1), a1 + hstep, voffA);
;             PG8_WAIT_V(8); PG8_WAIT_L(0); PG8_BAR; PG8_MMA(0, 0, At, B0); PG8_MMA(0, 1, At, B1); PG8_BAR; PG8_SCHED;
;             PG8_LDA(At, 0, 1); PG8_STAGE(PG8_SB(0, 0), b2, voffB); PG8_STAGE(PG8_SB(0, 1), b2 + hstep, voffB); PG8_STAGE(PG8_SA(0, 0), a2, voffA);
.LBB0_634:
	s_add_u32 s16, s14, 0x100
	s_addc_u32 s17, s15, 0
	s_cmp_eq_u32 s53, 28
	s_cselect_b32 s22, s49, s16
	s_cselect_b32 s23, s7, s17
	s_cselect_b32 s20, s50, s51
	s_cselect_b32 s21, s5, s52
	s_add_u32 s18, s22, 0x80
	s_addc_u32 s19, s23, 0
	s_add_i32 s54, 0, 0x10000
	s_add_i32 s55, 0, 0x14000
	ds_read_b128 v[82:85], v244
	ds_read_b128 v[86:89], v244 offset:1024
	ds_read_b128 v[90:93], v244 offset:2048
	ds_read_b128 v[94:97], v244 offset:3072
	ds_read_b128 v[146:149], v244 offset:16384
	ds_read_b128 v[150:153], v244 offset:17408
	ds_read_b128 v[154:157], v244 offset:18432
	ds_read_b128 v[158:161], v244 offset:19456
	s_add_u32 s14, s14, 0x80080
	s_addc_u32 s15, s15, 0
	ds_read_b128 v[178:181], v188
	ds_read_b128 v[190:193], v188 offset:1024
	ds_read_b128 v[194:197], v188 offset:2048
	ds_read_b128 v[198:201], v188 offset:3072
	ds_read_b128 v[202:205], v188 offset:4096
	ds_read_b128 v[206:209], v188 offset:5120
	ds_read_b128 v[210:213], v188 offset:6144
	ds_read_b128 v[220:223], v188 offset:7168
	s_add_i32 m0, s27, 0xc000
	s_nop 0
	global_load_lds_dwordx4 v1, s[14:15]
	s_add_i32 m0, s27, 0xe000
	s_nop 0
	global_load_lds_dwordx4 v164, s[14:15]
	s_waitcnt vmcnt(8)
	s_waitcnt lgkmcnt(0)
	s_barrier
	s_setprio 1
	s_waitcnt lgkmcnt(0)
	v_mfma_f32_16x16x32_bf16 v[142:145], v[82:85], v[178:181], v[142:145]
	v_mfma_f32_16x16x32_bf16 v[126:129], v[82:85], v[194:197], v[126:129]
	v_mfma_f32_16x16x32_bf16 v[142:145], v[86:89], v[190:193], v[142:145]
	v_mfma_f32_16x16x32_bf16 v[126:129], v[86:89], v[198:201], v[126:129]
	v_mfma_f32_16x16x32_bf16 v[138:141], v[90:93], v[178:181], v[138:141]
	v_mfma_f32_16x16x32_bf16 v[122:125], v[90:93], v[194:197], v[122:125]
	v_mfma_f32_16x16x32_bf16 v[138:141], v[94:97], v[190:193], v[138:141]
	v_mfma_f32_16x16x32_bf16 v[122:125], v[94:97], v[198:201], v[122:125]
	v_mfma_f32_16x16x32_bf16 v[110:113], v[82:85], v[202:205], v[110:113]
	v_mfma_f32_16x16x32_bf16 v[78:81], v[82:85], v[210:213], v[78:81]
	v_mfma_f32_16x16x32_bf16 v[110:113], v[86:89], v[206:209], v[110:113]
	v_mfma_f32_16x16x32_bf16 v[78:81], v[86:89], v[220:223], v[78:81]
	v_mfma_f32_16x16x32_bf16 v[106:109], v[90:93], v[202:205], v[106:109]
	v_mfma_f32_16x16x32_bf16 v[74:77], v[90:93], v[210:213], v[74:77]
	v_mfma_f32_16x16x32_bf16 v[106:109], v[94:97], v[206:209], v[106:109]
	v_mfma_f32_16x16x32_bf16 v[74:77], v[94:97], v[220:223], v[74:77]
	s_setprio 0
	s_setprio 1
	v_mfma_f32_16x16x32_bf16 v[134:137], v[146:149], v[178:181], v[134:137]
	v_mfma_f32_16x16x32_bf16 v[118:121], v[146:149], v[194:197], v[118:121]
	v_mfma_f32_16x16x32_bf16 v[134:137], v[150:153], v[190:193], v[134:137]
	v_mfma_f32_16x16x32_bf16 v[118:121], v[150:153], v[198:201], v[118:121]
	v_mfma_f32_16x16x32_bf16 v[130:133], v[154:157], v[178:181], v[130:133]
	v_mfma_f32_16x16x32_bf16 v[114:117], v[154:157], v[194:197], v[114:117]
	v_mfma_f32_16x16x32_bf16 v[130:133], v[158:161], v[190:193], v[130:133]
	v_mfma_f32_16x16x32_bf16 v[114:117], v[158:161], v[198:201], v[114:117]
	v_mfma_f32_16x16x32_bf16 v[102:105], v[146:149], v[202:205], v[102:105]
	v_mfma_f32_16x16x32_bf16 v[70:73], v[146:149], v[210:213], v[70:73]
	v_mfma_f32_16x16x32_bf16 v[102:105], v[150:153], v[206:209], v[102:105]
	v_mfma_f32_16x16x32_bf16 v[70:73], v[150:153], v[220:223], v[70:73]
	v_mfma_f32_16x16x32_bf16 v[98:101], v[154:157], v[202:205], v[98:101]
	v_mfma_f32_16x16x32_bf16 v[66:69], v[154:157], v[210:213], v[66:69]
	v_mfma_f32_16x16x32_bf16 v[98:101], v[158:161], v[206:209], v[98:101]
	v_mfma_f32_16x16x32_bf16 v[66:69], v[158:161], v[220:223], v[66:69]
	s_setprio 0
	s_barrier
	s_mov_b64 s[14:15], s[20:21]
	s_add_i32 s54, s54, s26
	ds_read_b128 v[178:181], v188 offset:16384
	ds_read_b128 v[190:193], v188 offset:17408
	ds_read_b128 v[194:197], v188 offset:18432
	ds_read_b128 v[198:201], v188 offset:19456
	ds_read_b128 v[202:205], v188 offset:20480
	ds_read_b128 v[206:209], v188 offset:21504
	ds_read_b128 v[210:213], v188 offset:22528
	ds_read_b128 v[220:223], v188 offset:23552
	s_mov_b32 m0, s54
	s_nop 0
	global_load_lds_dwordx4 v162, s[14:15]
	s_add_i32 m0, s54, 0x2000
	s_nop 0
	global_load_lds_dwordx4 v184, s[14:15]
	s_add_u32 s14, s20, 0x80000
	s_addc_u32 s15, s21, 0
	s_add_i32 s54, s55, s26
	s_mov_b32 m0, s54
	s_nop 0
	global_load_lds_dwordx4 v162, s[14:15]
	s_add_i32 m0, s54, 0x2000
	s_nop 0
	global_load_lds_dwordx4 v184, s[14:15]
	s_mov_b64 s[14:15], s[22:23]
	s_mov_b32 m0, s27
	s_nop 0
	global_load_lds_dwordx4 v1, s[14:15]
	s_mov_b32 m0, s28
	s_nop 0
	global_load_lds_dwordx4 v164, s[14:15]
	s_waitcnt vmcnt(8)
	s_waitcnt lgkmcnt(0)
	s_barrier
; #define PG8_STAGE(bufoff, gbase, voff) do { const char* gb_ = (const char*)(gbase); asm volatile("" : "+s"(gb_)); _Pragma("unroll") for (int _i = 0; _i < 2; ++_i) { unsigned vo_ = (voff)[_i]; asm volatile("" : "+v"(vo_));        \
;         __builtin_amdgcn_global_load_lds((const unsigned*)(gb_ + vo_), (PG8_LAS unsigned*)(lds + (bufoff) + ldsw + _i * 8192), 16, 0, 0); } } while (0)
; #define PG8_LDA(dst, b, h) do { _Pragma("unroll") for (int m = 0; m < 4; ++m) _Pragma("unroll") for (int k = 0; k < 2; ++k) dst[m][k] = *(const PG8_LAS bf16x8*)(lds + PG8_SA(b, h) + aoff + m * 2048 + k * 1024); } while (0)
; #define PG8_LDB(dst, b, h) do { _Pragma("unroll") for (int n = 0; n < 2; ++n) _Pragma("unroll") for (int k = 0; k < 2; ++k) dst[n][k] = *(const PG8_LAS bf16x8*)(lds + PG8_SB(b, h) + boff + n * 2048 + k * 1024); } while (0)
; #define PG8_MMA(ai, bj, At, Bt) do { __builtin_amdgcn_s_setprio(1); _Pragma("unroll") for (int m = 0; m < 4; ++m) _Pragma("unroll") for (int n = 0; n < 2; ++n) _Pragma("unroll") for (int k = 0; k < 2; ++k) \
;         acc[ai][bj][m][n] = __builtin_amdgcn_mfma_f32_16x16x32_bf16(Bt[n][k], At[m][k], acc[ai][bj][m][n], 0, 0, 0); __builtin_amdgcn_s_setprio(0); } while (0)
; #define PG8_WAIT_V(n) asm volatile("s_waitcnt vmcnt(" #n ")" ::: "memory")
; #define PG8_WAIT_L(n) asm volatile("s_waitcnt lgkmcnt(" #n ")" ::: "memory")
; #define PG8_BAR __builtin_amdgcn_s_barrier()
; #define PG8_SCHED __builtin_amdgcn_sched_barrier(0)
; template <class Epi, class Sched, bool ALIGN_EPI = false, bool SP2 = false>
; __device__ __forceinline__ void gemm_phase(PG8_LAS unsigned char* lds, const Gemm g, const Sched& S, const Epi& E) {
;     ...
;             PG8_WAIT_V(8); PG8_WAIT_L(0); PG8_BAR; PG8_MMA(1, 0, At, B0); PG8_MMA(1, 1, At, B1); PG8_BAR; PG8_SCHED;
;             PG8_LDB(B0, 1, 0); PG8_LDB(B1, 1, 1); PG8_SCHED; PG8_LDA(At, 1, 0); PG8_STAGE(PG8_SA(0, 1), a2 + hstep, voffA);
;             PG8_WAIT_V(8); PG8_WAIT_L(0); PG8_BAR; PG8_MMA(0, 0, At, B0); PG8_MMA(0, 1, At, B1); PG8_BAR; PG8_SCHED;
	s_setprio 1
	s_waitcnt lgkmcnt(0)
	v_mfma_f32_16x16x32_bf16 v[62:65], v[82:85], v[178:181], v[62:65]
	v_mfma_f32_16x16x32_bf16 v[46:49], v[82:85], v[194:197], v[46:49]
	v_mfma_f32_16x16x32_bf16 v[62:65], v[86:89], v[190:193], v[62:65]
	v_mfma_f32_16x16x32_bf16 v[46:49], v[86:89], v[198:201], v[46:49]
	v_mfma_f32_16x16x32_bf16 v[58:61], v[90:93], v[178:181], v[58:61]
	v_mfma_f32_16x16x32_bf16 v[42:45], v[90:93], v[194:197], v[42:45]
	v_mfma_f32_16x16x32_bf16 v[58:61], v[94:97], v[190:193], v[58:61]
	v_mfma_f32_16x16x32_bf16 v[42:45], v[94:97], v[198:201], v[42:45]
	v_mfma_f32_16x16x32_bf16 v[30:33], v[82:85], v[202:205], v[30:33]
	v_mfma_f32_16x16x32_bf16 v[14:17], v[82:85], v[210:213], v[14:17]
	v_mfma_f32_16x16x32_bf16 v[30:33], v[86:89], v[206:209], v[30:33]
	v_mfma_f32_16x16x32_bf16 v[14:17], v[86:89], v[220:223], v[14:17]
	v_mfma_f32_16x16x32_bf16 v[26:29], v[90:93], v[202:205], v[26:29]
	v_mfma_f32_16x16x32_bf16 v[10:13], v[90:93], v[210:213], v[10:13]
	v_mfma_f32_16x16x32_bf16 v[26:29], v[94:97], v[206:209], v[26:29]
	v_mfma_f32_16x16x32_bf16 v[10:13], v[94:97], v[220:223], v[10:13]
	s_setprio 0
	s_setprio 1
	v_mfma_f32_16x16x32_bf16 v[54:57], v[146:149], v[178:181], v[54:57]
	v_mfma_f32_16x16x32_bf16 v[38:41], v[146:149], v[194:197], v[38:41]
	v_mfma_f32_16x16x32_bf16 v[54:57], v[150:153], v[190:193], v[54:57]
	v_mfma_f32_16x16x32_bf16 v[38:41], v[150:153], v[198:201], v[38:41]
	v_mfma_f32_16x16x32_bf16 v[50:53], v[154:157], v[178:181], v[50:53]
	v_mfma_f32_16x16x32_bf16 v[34:37], v[154:157], v[194:197], v[34:37]
	v_mfma_f32_16x16x32_bf16 v[50:53], v[158:161], v[190:193], v[50:53]
	v_mfma_f32_16x16x32_bf16 v[34:37], v[158:161], v[198:201], v[34:37]
	v_mfma_f32_16x16x32_bf16 v[22:25], v[146:149], v[202:205], v[22:25]
	v_mfma_f32_16x16x32_bf16 v[6:9], v[146:149], v[210:213], v[6:9]
	v_mfma_f32_16x16x32_bf16 v[22:25], v[150:153], v[206:209], v[22:25]
	v_mfma_f32_16x16x32_bf16 v[6:9], v[150:153], v[220:223], v[6:9]
	v_mfma_f32_16x16x32_bf16 v[18:21], v[154:157], v[202:205], v[18:21]
	v_mfma_f32_16x16x32_bf16 v[2:5], v[154:157], v[210:213], v[2:5]
	v_mfma_f32_16x16x32_bf16 v[18:21], v[158:161], v[206:209], v[18:21]
	v_mfma_f32_16x16x32_bf16 v[2:5], v[158:161], v[220:223], v[2:5]
	s_setprio 0
	s_barrier
	s_add_i32 s54, 0, 0x18000
	s_add_i32 s55, 0, 0x1c000
	ds_read_b128 v[82:85], v244 offset:32768
	ds_read_b128 v[86:89], v244 offset:33792
	ds_read_b128 v[90:93], v244 offset:34816
	ds_read_b128 v[94:97], v244 offset:35840
	ds_read_b128 v[146:149], v244 offset:49152
	ds_read_b128 v[150:153], v244 offset:50176
	ds_read_b128 v[154:157], v244 offset:51200
	ds_read_b128 v[158:161], v244 offset:52224
	s_add_u32 s14, s22, 0x80000
	s_addc_u32 s15, s23, 0
	s_mov_b32 m0, s29
	ds_read_b128 v[178:181], v188 offset:32768
	ds_read_b128 v[190:193], v188 offset:33792
	ds_read_b128 v[194:197], v188 offset:34816
	ds_read_b128 v[198:201], v188 offset:35840
	ds_read_b128 v[202:205], v188 offset:36864
	ds_read_b128 v[206:209], v188 offset:37888
	ds_read_b128 v[210:213], v188 offset:38912
	ds_read_b128 v[220:223], v188 offset:39936
	s_nop 0
	global_load_lds_dwordx4 v1, s[14:15]
	s_mov_b32 m0, s33
	s_nop 0
	global_load_lds_dwordx4 v164, s[14:15]
	s_waitcnt vmcnt(8)
	s_waitcnt lgkmcnt(0)
	s_barrier
	s_setprio 1
	s_waitcnt lgkmcnt(0)
	v_mfma_f32_16x16x32_bf16 v[142:145], v[82:85], v[178:181], v[142:145]
	v_mfma_f32_16x16x32_bf16 v[126:129], v[82:85], v[194:197], v[126:129]
	v_mfma_f32_16x16x32_bf16 v[142:145], v[86:89], v[190:193], v[142:145]
	v_mfma_f32_16x16x32_bf16 v[126:129], v[86:89], v[198:201], v[126:129]
	v_mfma_f32_16x16x32_bf16 v[138:141], v[90:93], v[178:181], v[138:141]
	v_mfma_f32_16x16x32_bf16 v[122:125], v[90:93], v[194:197], v[122:125]
	v_mfma_f32_16x16x32_bf16 v[138:141], v[94:97], v[190:193], v[138:141]
	v_mfma_f32_16x16x32_bf16 v[122:125], v[94:97], v[198:201], v[122:125]
	v_mfma_f32_16x16x32_bf16 v[110:113], v[82:85], v[202:205], v[110:113]
	v_mfma_f32_16x16x32_bf16 v[78:81], v[82:85], v[210:213], v[78:81]
	v_mfma_f32_16x16x32_bf16 v[110:113], v[86:89], v[206:209], v[110:113]
	v_mfma_f32_16x16x32_bf16 v[78:81], v[86:89], v[220:223], v[78:81]
	v_mfma_f32_16x16x32_bf16 v[106:109], v[90:93], v[202:205], v[106:109]
	v_mfma_f32_16x16x32_bf16 v[74:77], v[90:93], v[210:213], v[74:77]
	v_mfma_f32_16x16x32_bf16 v[106:109], v[94:97], v[206:209], v[106:109]
	v_mfma_f32_16x16x32_bf16 v[74:77], v[94:97], v[220:223], v[74:77]
	s_setprio 0
	s_setprio 1
	v_mfma_f32_16x16x32_bf16 v[134:137], v[146:149], v[178:181], v[134:137]
	v_mfma_f32_16x16x32_bf16 v[118:121], v[146:149], v[194:197], v[118:121]
	v_mfma_f32_16x16x32_bf16 v[134:137], v[150:153], v[190:193], v[134:137]
	v_mfma_f32_16x16x32_bf16 v[118:121], v[150:153], v[198:201], v[118:121]
	v_mfma_f32_16x16x32_bf16 v[130:133], v[154:157], v[178:181], v[130:133]
	v_mfma_f32_16x16x32_bf16 v[114:117], v[154:157], v[194:197], v[114:117]
	v_mfma_f32_16x16x32_bf16 v[130:133], v[158:161], v[190:193], v[130:133]
	v_mfma_f32_16x16x32_bf16 v[114:117], v[158:161], v[198:201], v[114:117]
	v_mfma_f32_16x16x32_bf16 v[102:105], v[146:149], v[202:205], v[102:105]
	v_mfma_f32_16x16x32_bf16 v[70:73], v[146:149], v[210:213], v[70:73]
	v_mfma_f32_16x16x32_bf16 v[102:105], v[150:153], v[206:209], v[102:105]
	v_mfma_f32_16x16x32_bf16 v[70:73], v[150:153], v[220:223], v[70:73]
	v_mfma_f32_16x16x32_bf16 v[98:101], v[154:157], v[202:205], v[98:101]
	v_mfma_f32_16x16x32_bf16 v[66:69], v[154:157], v[210:213], v[66:69]
	v_mfma_f32_16x16x32_bf16 v[98:101], v[158:161], v[206:209], v[98:101]
	v_mfma_f32_16x16x32_bf16 v[66:69], v[158:161], v[220:223], v[66:69]
	s_setprio 0
	s_barrier
; #define PG8_STAGE(bufoff, gbase, voff) do { const char* gb_ = (const char*)(gbase); asm volatile("" : "+s"(gb_)); _Pragma("unroll") for (int _i = 0; _i < 2; ++_i) { unsigned vo_ = (voff)[_i]; asm volatile("" : "+v"(vo_));        \
;         __builtin_amdgcn_global_load_lds((const unsigned*)(gb_ + vo_), (PG8_LAS unsigned*)(lds + (bufoff) + ldsw + _i * 8192), 16, 0, 0); } } while (0)
; #define PG8_LDA(dst, b, h) do { _Pragma("unroll") for (int m = 0; m < 4; ++m) _Pragma("unroll") for (int k = 0; k < 2; ++k) dst[m][k] = *(const PG8_LAS bf16x8*)(lds + PG8_SA(b, h) + aoff + m * 2048 + k * 1024); } while (0)
; #define PG8_MMA(ai, bj, At, Bt) do { __builtin_amdgcn_s_setprio(1); _Pragma("unroll") for (int m = 0; m < 4; ++m) _Pragma("unroll") for (int n = 0; n < 2; ++n) _Pragma("unroll") for (int k = 0; k < 2; ++k) \
;         acc[ai][bj][m][n] = __builtin_amdgcn_mfma_f32_16x16x32_bf16(Bt[n][k], At[m][k], acc[ai][bj][m][n], 0, 0, 0); __builtin_amdgcn_s_setprio(0); } while (0)
; #define PG8_WAIT_V(n) asm volatile("s_waitcnt vmcnt(" #n ")" ::: "memory")
; #define PG8_WAIT_L(n) asm volatile("s_waitcnt lgkmcnt(" #n ")" ::: "memory")
; #define PG8_BAR __builtin_amdgcn_s_barrier()
; #define PG8_SCHED __builtin_amdgcn_sched_barrier(0)
; template <class Epi, class Sched, bool ALIGN_EPI = false, bool SP2 = false>
; __device__ __forceinline__ void gemm_phase(PG8_LAS unsigned char* lds, const Gemm g, const Sched& S, const Epi& E) {
;     ...
;             PG8_LDA(At, 1, 1); PG8_STAGE(PG8_SB(1, 0), b3, voffB); PG8_STAGE(PG8_SB(1, 1), b3 + hstep, voffB); PG8_STAGE(PG8_SA(1, 0), a3, voffA);
;             PG8_WAIT_V(8); PG8_WAIT_L(0); PG8_BAR; PG8_MMA(1, 0, At, B0); PG8_MMA(1, 1, At, B1); PG8_BAR; PG8_SCHED;
;     ...
;         if constexpr (ALIGN_EPI) { if (wr == 0) PG8_BAR; }
	s_add_u32 s14, s20, 0x80
	s_addc_u32 s15, s21, 0
	s_add_i32 s22, s54, s26
	ds_read_b128 v[178:181], v188 offset:49152
	ds_read_b128 v[190:193], v188 offset:50176
	ds_read_b128 v[194:197], v188 offset:51200
	ds_read_b128 v[198:201], v188 offset:52224
	ds_read_b128 v[202:205], v188 offset:53248
	ds_read_b128 v[206:209], v188 offset:54272
	ds_read_b128 v[210:213], v188 offset:55296
	ds_read_b128 v[220:223], v188 offset:56320
	s_mov_b32 m0, s22
	s_nop 0
	global_load_lds_dwordx4 v162, s[14:15]
	s_add_i32 m0, s22, 0x2000
	s_nop 0
	global_load_lds_dwordx4 v184, s[14:15]
	s_add_u32 s14, s20, 0x80080
	s_addc_u32 s15, s21, 0
	s_add_i32 s20, s55, s26
	s_mov_b32 m0, s20
	s_nop 0
	global_load_lds_dwordx4 v162, s[14:15]
	s_add_i32 m0, s20, 0x2000
	s_nop 0
	global_load_lds_dwordx4 v184, s[14:15]
	s_mov_b32 m0, s38
	s_nop 0
	global_load_lds_dwordx4 v1, s[18:19]
	s_mov_b32 m0, s39
	s_nop 0
	global_load_lds_dwordx4 v164, s[18:19]
	s_waitcnt vmcnt(8)
	s_waitcnt lgkmcnt(0)
	s_barrier
	s_setprio 1
	s_waitcnt lgkmcnt(0)
	v_mfma_f32_16x16x32_bf16 v[62:65], v[82:85], v[178:181], v[62:65]
	v_mfma_f32_16x16x32_bf16 v[46:49], v[82:85], v[194:197], v[46:49]
	v_mfma_f32_16x16x32_bf16 v[62:65], v[86:89], v[190:193], v[62:65]
	v_mfma_f32_16x16x32_bf16 v[46:49], v[86:89], v[198:201], v[46:49]
	v_mfma_f32_16x16x32_bf16 v[58:61], v[90:93], v[178:181], v[58:61]
	v_mfma_f32_16x16x32_bf16 v[42:45], v[90:93], v[194:197], v[42:45]
	v_mfma_f32_16x16x32_bf16 v[58:61], v[94:97], v[190:193], v[58:61]
	v_mfma_f32_16x16x32_bf16 v[42:45], v[94:97], v[198:201], v[42:45]
	v_mfma_f32_16x16x32_bf16 v[30:33], v[82:85], v[202:205], v[30:33]
	v_mfma_f32_16x16x32_bf16 v[14:17], v[82:85], v[210:213], v[14:17]
	v_mfma_f32_16x16x32_bf16 v[30:33], v[86:89], v[206:209], v[30:33]
	v_mfma_f32_16x16x32_bf16 v[14:17], v[86:89], v[220:223], v[14:17]
	v_mfma_f32_16x16x32_bf16 v[26:29], v[90:93], v[202:205], v[26:29]
	v_mfma_f32_16x16x32_bf16 v[10:13], v[90:93], v[210:213], v[10:13]
	v_mfma_f32_16x16x32_bf16 v[26:29], v[94:97], v[206:209], v[26:29]
	v_mfma_f32_16x16x32_bf16 v[10:13], v[94:97], v[220:223], v[10:13]
	s_setprio 0
	s_setprio 1
	v_mfma_f32_16x16x32_bf16 v[54:57], v[146:149], v[178:181], v[54:57]
	v_mfma_f32_16x16x32_bf16 v[38:41], v[146:149], v[194:197], v[38:41]
	v_mfma_f32_16x16x32_bf16 v[54:57], v[150:153], v[190:193], v[54:57]
	v_mfma_f32_16x16x32_bf16 v[38:41], v[150:153], v[198:201], v[38:41]
	v_mfma_f32_16x16x32_bf16 v[50:53], v[154:157], v[178:181], v[50:53]
	v_mfma_f32_16x16x32_bf16 v[34:37], v[154:157], v[194:197], v[34:37]
	v_mfma_f32_16x16x32_bf16 v[50:53], v[158:161], v[190:193], v[50:53]
	v_mfma_f32_16x16x32_bf16 v[34:37], v[158:161], v[198:201], v[34:37]
	v_mfma_f32_16x16x32_bf16 v[22:25], v[146:149], v[202:205], v[22:25]
	v_mfma_f32_16x16x32_bf16 v[6:9], v[146:149], v[210:213], v[6:9]
	v_mfma_f32_16x16x32_bf16 v[22:25], v[150:153], v[206:209], v[22:25]
	v_mfma_f32_16x16x32_bf16 v[6:9], v[150:153], v[220:223], v[6:9]
	v_mfma_f32_16x16x32_bf16 v[18:21], v[154:157], v[202:205], v[18:21]
	v_mfma_f32_16x16x32_bf16 v[2:5], v[154:157], v[210:213], v[2:5]
	v_mfma_f32_16x16x32_bf16 v[18:21], v[158:161], v[206:209], v[18:21]
	v_mfma_f32_16x16x32_bf16 v[2:5], v[158:161], v[220:223], v[2:5]
	s_setprio 0
	s_barrier
	s_add_i32 s53, s53, 2
	s_add_u32 s51, s51, 0x100
	s_addc_u32 s52, s52, 0
	s_cmp_gt_u32 s53, 29
	s_mov_b64 s[14:15], s[16:17]
	s_cbranch_scc0 .LBB0_634
	s_and_b64 vcc, exec, s[2:3]
	s_cbranch_vccz .LBB0_637
	s_barrier

; #define PG8_STAGE(bufoff, gbase, voff) do { const char* gb_ = (const char*)(gbase); asm volatile("" : "+s"(gb_)); _Pragma("unroll") for (int _i = 0; _i < 2; ++_i) { unsigned vo_ = (voff)[_i]; asm volatile("" : "+v"(vo_));        \
;         __builtin_amdgcn_global_load_lds((const unsigned*)(gb_ + vo_), (PG8_LAS unsigned*)(lds + (bufoff) + ldsw + _i * 8192), 16, 0, 0); } } while (0)
; #define PG8_LDA(dst, b, h) do { _Pragma("unroll") for (int m = 0; m < 4; ++m) _Pragma("unroll") for (int k = 0; k < 2; ++k) dst[m][k] = *(const PG8_LAS bf16x8*)(lds + PG8_SA(b, h) + aoff + m * 2048 + k * 1024); } while (0)
; #define PG8_LDB(dst, b, h) do { _Pragma("unroll") for (int n = 0; n < 2; ++n) _Pragma("unroll") for (int k = 0; k < 2; ++k) dst[n][k] = *(const PG8_LAS bf16x8*)(lds + PG8_SB(b, h) + boff + n * 2048 + k * 1024); } while (0)
; #define PG8_MMA(ai, bj, At, Bt) do { __builtin_amdgcn_s_setprio(1); _Pragma("unroll") for (int m = 0; m < 4; ++m) _Pragma("unroll") for (int n = 0; n < 2; ++n) _Pragma("unroll") for (int k = 0; k < 2; ++k) \
;         acc[ai][bj][m][n] = __builtin_amdgcn_mfma_f32_16x16x32_bf16(Bt[n][k], At[m][k], acc[ai][bj][m][n], 0, 0, 0); __builtin_amdgcn_s_setprio(0); } while (0)
; #define PG8_WAIT_V(n) asm volatile("s_waitcnt vmcnt(" #n ")" ::: "memory")
; #define PG8_WAIT_L(n) asm volatile("s_waitcnt lgkmcnt(" #n ")" ::: "memory")
; template <class Epi, class Sched, bool ALIGN_EPI = false, bool SP2 = false>
; __device__ __forceinline__ void gemm_phase(PG8_LAS unsigned char* lds, const Gemm g, const Sched& S, const Epi& E) {
;     ...
;             const bool last = (t == nt - 2);
;             const char* a1 = cA + (size_t)(t + 1) * kstep;
;             const char* a2 = last ? nA : cA + (size_t)(t + 2) * kstep; const char* b2 = last ? nB : cB + (size_t)(t + 2) * kstep;
;             const char* a3 = a2 + kstep; const char* b3 = b2 + kstep;
;             if (last && has_next) S.a_ready(nxt);
;             if constexpr (SP2) {
;             PG8_LDB(B0, 0, 0); PG8_LDB(B1, 0, 1); PG8_SCHED; PG8_LDA(At, 0, 0); PG8_STAGE(PG8_SA(1, 1), a1 + hstep, voffA);
;             PG8_WAIT_V(8); PG8_WAIT_L(0); PG8_BAR; PG8_MMA(0, 0, At, B0); PG8_MMA(0, 1, At, B1); PG8_BAR; PG8_SCHED;
;             PG8_LDA(At, 0, 1); PG8_STAGE(PG8_SB(0, 0), b2, voffB); PG8_STAGE(PG8_SB(0, 1), b2 + hstep, voffB); PG8_STAGE(PG8_SA(0, 0), a2, voffA);
.LBB0_707:
	s_add_u32 s2, s4, 0x100
	s_addc_u32 s3, s5, 0
	s_cmpk_eq_i32 s35, 0x54
	s_cselect_b32 s10, s52, s2
	s_cselect_b32 s11, s53, s3
	s_cselect_b32 s8, s42, s31
	s_cselect_b32 s9, s43, s34
	s_add_u32 s6, s10, 0x80
	s_addc_u32 s7, s11, 0
	s_add_i32 s38, 0, 0x10000
	s_add_i32 s39, 0, 0x14000
	ds_read_b128 v[34:37], v244
	ds_read_b128 v[38:41], v244 offset:1024
	ds_read_b128 v[98:101], v244 offset:2048
	ds_read_b128 v[102:105], v244 offset:3072
	ds_read_b128 v[146:149], v244 offset:16384
	ds_read_b128 v[150:153], v244 offset:17408
	ds_read_b128 v[154:157], v244 offset:18432
	ds_read_b128 v[158:161], v244 offset:19456
	s_add_u32 s4, s4, 0x160080
	s_addc_u32 s5, s5, 0
	ds_read_b128 v[178:181], v194
	ds_read_b128 v[182:185], v194 offset:1024
	ds_read_b128 v[186:189], v194 offset:2048
	ds_read_b128 v[196:199], v194 offset:3072
	ds_read_b128 v[200:203], v194 offset:4096
	ds_read_b128 v[204:207], v194 offset:5120
	ds_read_b128 v[208:211], v194 offset:6144
	ds_read_b128 v[212:215], v194 offset:7168
	s_add_i32 m0, s16, 0xc000
	s_nop 0
	global_load_lds_dwordx4 v1, s[4:5]
	s_add_i32 m0, s16, 0xe000
	s_nop 0
	global_load_lds_dwordx4 v164, s[4:5]
	s_waitcnt vmcnt(8)
	s_waitcnt lgkmcnt(0)
	s_barrier
	s_setprio 1
	s_waitcnt lgkmcnt(0)
	v_mfma_f32_16x16x32_bf16 v[142:145], v[34:37], v[178:181], v[142:145]
	v_mfma_f32_16x16x32_bf16 v[134:137], v[34:37], v[186:189], v[134:137]
	v_mfma_f32_16x16x32_bf16 v[142:145], v[38:41], v[182:185], v[142:145]
	v_mfma_f32_16x16x32_bf16 v[134:137], v[38:41], v[196:199], v[134:137]
	v_mfma_f32_16x16x32_bf16 v[138:141], v[98:101], v[178:181], v[138:141]
	v_mfma_f32_16x16x32_bf16 v[130:133], v[98:101], v[186:189], v[130:133]
	v_mfma_f32_16x16x32_bf16 v[138:141], v[102:105], v[182:185], v[138:141]
	v_mfma_f32_16x16x32_bf16 v[130:133], v[102:105], v[196:199], v[130:133]
	v_mfma_f32_16x16x32_bf16 v[126:129], v[34:37], v[200:203], v[126:129]
	v_mfma_f32_16x16x32_bf16 v[118:121], v[34:37], v[208:211], v[118:121]
	v_mfma_f32_16x16x32_bf16 v[126:129], v[38:41], v[204:207], v[126:129]
	v_mfma_f32_16x16x32_bf16 v[118:121], v[38:41], v[212:215], v[118:121]
	v_mfma_f32_16x16x32_bf16 v[122:125], v[98:101], v[200:203], v[122:125]
	v_mfma_f32_16x16x32_bf16 v[114:117], v[98:101], v[208:211], v[114:117]
	v_mfma_f32_16x16x32_bf16 v[122:125], v[102:105], v[204:207], v[122:125]
	v_mfma_f32_16x16x32_bf16 v[114:117], v[102:105], v[212:215], v[114:117]
	s_setprio 0
	s_setprio 1
	v_mfma_f32_16x16x32_bf16 v[70:73], v[146:149], v[178:181], v[70:73]
	v_mfma_f32_16x16x32_bf16 v[62:65], v[146:149], v[186:189], v[62:65]
	v_mfma_f32_16x16x32_bf16 v[70:73], v[150:153], v[182:185], v[70:73]
	v_mfma_f32_16x16x32_bf16 v[62:65], v[150:153], v[196:199], v[62:65]
	v_mfma_f32_16x16x32_bf16 v[66:69], v[154:157], v[178:181], v[66:69]
	v_mfma_f32_16x16x32_bf16 v[58:61], v[154:157], v[186:189], v[58:61]
	v_mfma_f32_16x16x32_bf16 v[66:69], v[158:161], v[182:185], v[66:69]
	v_mfma_f32_16x16x32_bf16 v[58:61], v[158:161], v[196:199], v[58:61]
	v_mfma_f32_16x16x32_bf16 v[54:57], v[146:149], v[200:203], v[54:57]
	v_mfma_f32_16x16x32_bf16 v[46:49], v[146:149], v[208:211], v[46:49]
	v_mfma_f32_16x16x32_bf16 v[54:57], v[150:153], v[204:207], v[54:57]
	v_mfma_f32_16x16x32_bf16 v[46:49], v[150:153], v[212:215], v[46:49]
	v_mfma_f32_16x16x32_bf16 v[50:53], v[154:157], v[200:203], v[50:53]
	v_mfma_f32_16x16x32_bf16 v[42:45], v[154:157], v[208:211], v[42:45]
	v_mfma_f32_16x16x32_bf16 v[50:53], v[158:161], v[204:207], v[50:53]
	v_mfma_f32_16x16x32_bf16 v[42:45], v[158:161], v[212:215], v[42:45]
	s_setprio 0
	s_barrier
	s_mov_b64 s[4:5], s[8:9]
	s_add_i32 s38, s38, s15
	ds_read_b128 v[178:181], v194 offset:16384
	ds_read_b128 v[182:185], v194 offset:17408
	ds_read_b128 v[186:189], v194 offset:18432
	ds_read_b128 v[196:199], v194 offset:19456
	ds_read_b128 v[200:203], v194 offset:20480
	ds_read_b128 v[204:207], v194 offset:21504
	ds_read_b128 v[208:211], v194 offset:22528
	ds_read_b128 v[212:215], v194 offset:23552
	s_mov_b32 m0, s38
	s_nop 0
	global_load_lds_dwordx4 v162, s[4:5]
	s_add_i32 m0, s38, 0x2000
	s_nop 0
	global_load_lds_dwordx4 v190, s[4:5]
	s_add_u32 s4, s8, 0x160000
	s_addc_u32 s5, s9, 0
	s_add_i32 s38, s39, s15
	s_mov_b32 m0, s38
	s_nop 0
	global_load_lds_dwordx4 v162, s[4:5]
	s_add_i32 m0, s38, 0x2000
	s_nop 0
	global_load_lds_dwordx4 v190, s[4:5]
	s_mov_b64 s[4:5], s[10:11]
	s_mov_b32 m0, s16
	s_nop 0
	global_load_lds_dwordx4 v1, s[4:5]
	s_mov_b32 m0, s17
	s_nop 0
	global_load_lds_dwordx4 v164, s[4:5]
	s_waitcnt vmcnt(8)
	s_waitcnt lgkmcnt(0)
	s_barrier
; #define PG8_STAGE(bufoff, gbase, voff) do { const char* gb_ = (const char*)(gbase); asm volatile("" : "+s"(gb_)); _Pragma("unroll") for (int _i = 0; _i < 2; ++_i) { unsigned vo_ = (voff)[_i]; asm volatile("" : "+v"(vo_));        \
;         __builtin_amdgcn_global_load_lds((const unsigned*)(gb_ + vo_), (PG8_LAS unsigned*)(lds + (bufoff) + ldsw + _i * 8192), 16, 0, 0); } } while (0)
; #define PG8_LDA(dst, b, h) do { _Pragma("unroll") for (int m = 0; m < 4; ++m) _Pragma("unroll") for (int k = 0; k < 2; ++k) dst[m][k] = *(const PG8_LAS bf16x8*)(lds + PG8_SA(b, h) + aoff + m * 2048 + k * 1024); } while (0)
; #define PG8_LDB(dst, b, h) do { _Pragma("unroll") for (int n = 0; n < 2; ++n) _Pragma("unroll") for (int k = 0; k < 2; ++k) dst[n][k] = *(const PG8_LAS bf16x8*)(lds + PG8_SB(b, h) + boff + n * 2048 + k * 1024); } while (0)
; #define PG8_MMA(ai, bj, At, Bt) do { __builtin_amdgcn_s_setprio(1); _Pragma("unroll") for (int m = 0; m < 4; ++m) _Pragma("unroll") for (int n = 0; n < 2; ++n) _Pragma("unroll") for (int k = 0; k < 2; ++k) \
;         acc[ai][bj][m][n] = __builtin_amdgcn_mfma_f32_16x16x32_bf16(Bt[n][k], At[m][k], acc[ai][bj][m][n], 0, 0, 0); __builtin_amdgcn_s_setprio(0); } while (0)
; #define PG8_WAIT_V(n) asm volatile("s_waitcnt vmcnt(" #n ")" ::: "memory")
; #define PG8_WAIT_L(n) asm volatile("s_waitcnt lgkmcnt(" #n ")" ::: "memory")
; #define PG8_BAR __builtin_amdgcn_s_barrier()
; #define PG8_SCHED __builtin_amdgcn_sched_barrier(0)
; template <class Epi, class Sched, bool ALIGN_EPI = false, bool SP2 = false>
; __device__ __forceinline__ void gemm_phase(PG8_LAS unsigned char* lds, const Gemm g, const Sched& S, const Epi& E) {
;     ...
;             PG8_WAIT_V(8); PG8_WAIT_L(0); PG8_BAR; PG8_MMA(1, 0, At, B0); PG8_MMA(1, 1, At, B1); PG8_BAR; PG8_SCHED;
;             PG8_LDB(B0, 1, 0); PG8_LDB(B1, 1, 1); PG8_SCHED; PG8_LDA(At, 1, 0); PG8_STAGE(PG8_SA(0, 1), a2 + hstep, voffA);
;             PG8_WAIT_V(8); PG8_WAIT_L(0); PG8_BAR; PG8_MMA(0, 0, At, B0); PG8_MMA(0, 1, At, B1); PG8_BAR; PG8_SCHED;
	s_setprio 1
	s_waitcnt lgkmcnt(0)
	v_mfma_f32_16x16x32_bf16 v[110:113], v[34:37], v[178:181], v[110:113]
	v_mfma_f32_16x16x32_bf16 v[94:97], v[34:37], v[186:189], v[94:97]
	v_mfma_f32_16x16x32_bf16 v[110:113], v[38:41], v[182:185], v[110:113]
	v_mfma_f32_16x16x32_bf16 v[94:97], v[38:41], v[196:199], v[94:97]
	v_mfma_f32_16x16x32_bf16 v[106:109], v[98:101], v[178:181], v[106:109]
	v_mfma_f32_16x16x32_bf16 v[90:93], v[98:101], v[186:189], v[90:93]
	v_mfma_f32_16x16x32_bf16 v[106:109], v[102:105], v[182:185], v[106:109]
	v_mfma_f32_16x16x32_bf16 v[90:93], v[102:105], v[196:199], v[90:93]
	v_mfma_f32_16x16x32_bf16 v[86:89], v[34:37], v[200:203], v[86:89]
	v_mfma_f32_16x16x32_bf16 v[86:89], v[38:41], v[204:207], v[86:89]
	v_mfma_f32_16x16x32_bf16 v[34:37], v[34:37], v[208:211], v[78:81]
	v_mfma_f32_16x16x32_bf16 v[34:37], v[38:41], v[212:215], v[34:37]
	v_mfma_f32_16x16x32_bf16 v[82:85], v[98:101], v[200:203], v[82:85]
	v_mfma_f32_16x16x32_bf16 v[38:41], v[98:101], v[208:211], v[74:77]
	v_mfma_f32_16x16x32_bf16 v[82:85], v[102:105], v[204:207], v[82:85]
	v_mfma_f32_16x16x32_bf16 v[38:41], v[102:105], v[212:215], v[38:41]
	s_setprio 0
	s_setprio 1
	v_mfma_f32_16x16x32_bf16 v[30:33], v[146:149], v[178:181], v[30:33]
	v_mfma_f32_16x16x32_bf16 v[22:25], v[146:149], v[186:189], v[22:25]
	v_mfma_f32_16x16x32_bf16 v[30:33], v[150:153], v[182:185], v[30:33]
	v_mfma_f32_16x16x32_bf16 v[22:25], v[150:153], v[196:199], v[22:25]
	v_mfma_f32_16x16x32_bf16 v[26:29], v[154:157], v[178:181], v[26:29]
	v_mfma_f32_16x16x32_bf16 v[18:21], v[154:157], v[186:189], v[18:21]
	v_mfma_f32_16x16x32_bf16 v[26:29], v[158:161], v[182:185], v[26:29]
	v_mfma_f32_16x16x32_bf16 v[18:21], v[158:161], v[196:199], v[18:21]
	v_mfma_f32_16x16x32_bf16 v[14:17], v[146:149], v[200:203], v[14:17]
	v_mfma_f32_16x16x32_bf16 v[6:9], v[146:149], v[208:211], v[6:9]
	v_mfma_f32_16x16x32_bf16 v[14:17], v[150:153], v[204:207], v[14:17]
	v_mfma_f32_16x16x32_bf16 v[6:9], v[150:153], v[212:215], v[6:9]
	v_mfma_f32_16x16x32_bf16 v[10:13], v[154:157], v[200:203], v[10:13]
	v_mfma_f32_16x16x32_bf16 v[2:5], v[154:157], v[208:211], v[2:5]
	v_mfma_f32_16x16x32_bf16 v[10:13], v[158:161], v[204:207], v[10:13]
	v_mfma_f32_16x16x32_bf16 v[2:5], v[158:161], v[212:215], v[2:5]
	s_setprio 0
	s_barrier
	s_add_i32 s38, 0, 0x18000
	s_add_i32 s39, 0, 0x1c000
	ds_read_b128 v[74:77], v244 offset:32768
	ds_read_b128 v[78:81], v244 offset:33792
	ds_read_b128 v[98:101], v244 offset:34816
	ds_read_b128 v[102:105], v244 offset:35840
	ds_read_b128 v[146:149], v244 offset:49152
	ds_read_b128 v[150:153], v244 offset:50176
	ds_read_b128 v[154:157], v244 offset:51200
	ds_read_b128 v[158:161], v244 offset:52224
	s_add_u32 s4, s10, 0x160000
	s_addc_u32 s5, s11, 0
	s_mov_b32 m0, s18
	ds_read_b128 v[178:181], v194 offset:32768
	ds_read_b128 v[182:185], v194 offset:33792
	ds_read_b128 v[186:189], v194 offset:34816
	ds_read_b128 v[196:199], v194 offset:35840
	ds_read_b128 v[200:203], v194 offset:36864
	ds_read_b128 v[204:207], v194 offset:37888
	ds_read_b128 v[208:211], v194 offset:38912
	ds_read_b128 v[212:215], v194 offset:39936
	s_nop 0
	global_load_lds_dwordx4 v1, s[4:5]
	s_mov_b32 m0, s19
	s_nop 0
	global_load_lds_dwordx4 v164, s[4:5]
	s_waitcnt vmcnt(8)
	s_waitcnt lgkmcnt(0)
	s_barrier
	s_setprio 1
	s_waitcnt lgkmcnt(0)
	v_mfma_f32_16x16x32_bf16 v[142:145], v[74:77], v[178:181], v[142:145]
	v_mfma_f32_16x16x32_bf16 v[134:137], v[74:77], v[186:189], v[134:137]
	v_mfma_f32_16x16x32_bf16 v[142:145], v[78:81], v[182:185], v[142:145]
	v_mfma_f32_16x16x32_bf16 v[134:137], v[78:81], v[196:199], v[134:137]
	v_mfma_f32_16x16x32_bf16 v[138:141], v[98:101], v[178:181], v[138:141]
	v_mfma_f32_16x16x32_bf16 v[130:133], v[98:101], v[186:189], v[130:133]
	v_mfma_f32_16x16x32_bf16 v[138:141], v[102:105], v[182:185], v[138:141]
	v_mfma_f32_16x16x32_bf16 v[130:133], v[102:105], v[196:199], v[130:133]
	v_mfma_f32_16x16x32_bf16 v[126:129], v[74:77], v[200:203], v[126:129]
	v_mfma_f32_16x16x32_bf16 v[118:121], v[74:77], v[208:211], v[118:121]
	v_mfma_f32_16x16x32_bf16 v[126:129], v[78:81], v[204:207], v[126:129]
	v_mfma_f32_16x16x32_bf16 v[118:121], v[78:81], v[212:215], v[118:121]
	v_mfma_f32_16x16x32_bf16 v[122:125], v[98:101], v[200:203], v[122:125]
	v_mfma_f32_16x16x32_bf16 v[114:117], v[98:101], v[208:211], v[114:117]
	v_mfma_f32_16x16x32_bf16 v[122:125], v[102:105], v[204:207], v[122:125]
	v_mfma_f32_16x16x32_bf16 v[114:117], v[102:105], v[212:215], v[114:117]
	s_setprio 0
	s_setprio 1
	v_mfma_f32_16x16x32_bf16 v[70:73], v[146:149], v[178:181], v[70:73]
	v_mfma_f32_16x16x32_bf16 v[62:65], v[146:149], v[186:189], v[62:65]
	v_mfma_f32_16x16x32_bf16 v[70:73], v[150:153], v[182:185], v[70:73]
	v_mfma_f32_16x16x32_bf16 v[62:65], v[150:153], v[196:199], v[62:65]
	v_mfma_f32_16x16x32_bf16 v[66:69], v[154:157], v[178:181], v[66:69]
	v_mfma_f32_16x16x32_bf16 v[58:61], v[154:157], v[186:189], v[58:61]
	v_mfma_f32_16x16x32_bf16 v[66:69], v[158:161], v[182:185], v[66:69]
	v_mfma_f32_16x16x32_bf16 v[58:61], v[158:161], v[196:199], v[58:61]
	v_mfma_f32_16x16x32_bf16 v[54:57], v[146:149], v[200:203], v[54:57]
	v_mfma_f32_16x16x32_bf16 v[46:49], v[146:149], v[208:211], v[46:49]
	v_mfma_f32_16x16x32_bf16 v[54:57], v[150:153], v[204:207], v[54:57]
	v_mfma_f32_16x16x32_bf16 v[46:49], v[150:153], v[212:215], v[46:49]
	v_mfma_f32_16x16x32_bf16 v[50:53], v[154:157], v[200:203], v[50:53]
	v_mfma_f32_16x16x32_bf16 v[42:45], v[154:157], v[208:211], v[42:45]
	v_mfma_f32_16x16x32_bf16 v[50:53], v[158:161], v[204:207], v[50:53]
	v_mfma_f32_16x16x32_bf16 v[42:45], v[158:161], v[212:215], v[42:45]
	s_setprio 0
	s_barrier
; #define PG8_STAGE(bufoff, gbase, voff) do { const char* gb_ = (const char*)(gbase); asm volatile("" : "+s"(gb_)); _Pragma("unroll") for (int _i = 0; _i < 2; ++_i) { unsigned vo_ = (voff)[_i]; asm volatile("" : "+v"(vo_));        \
;         __builtin_amdgcn_global_load_lds((const unsigned*)(gb_ + vo_), (PG8_LAS unsigned*)(lds + (bufoff) + ldsw + _i * 8192), 16, 0, 0); } } while (0)
; #define PG8_LDA(dst, b, h) do { _Pragma("unroll") for (int m = 0; m < 4; ++m) _Pragma("unroll") for (int k = 0; k < 2; ++k) dst[m][k] = *(const PG8_LAS bf16x8*)(lds + PG8_SA(b, h) + aoff + m * 2048 + k * 1024); } while (0)
; #define PG8_WAIT_V(n) asm volatile("s_waitcnt vmcnt(" #n ")" ::: "memory")
; #define PG8_WAIT_L(n) asm volatile("s_waitcnt lgkmcnt(" #n ")" ::: "memory")
; #define PG8_BAR __builtin_amdgcn_s_barrier()
; #define PG8_SCHED __builtin_amdgcn_sched_barrier(0)
;     __device__ __forceinline__ void operator()(const f32x4 (&acc)[2][2][4][2], const Unit& u, int wr, int wc, int fr, int fq) const {
;         const int row0 = u.pm * BM + wr * 64 + fr, col0 = u.pn * BM + wc * 32 + 8 * fq, b = (u.pm * BM) / rows_per_batch;
;         const float* g = gate + (size_t)b * gate_bstride + col0;
;         float ssq[2][4];
; #pragma unroll
;         for (int ai = 0; ai < 2; ++ai)
; #pragma unroll
;             for (int m = 0; m < 4; ++m) ssq[ai][m] = 0.f;
;         f32x4 gv[2][2], Gv[2][2];
; #pragma unroll
;         for (int bj = 0; bj < 2; ++bj) { gv[bj][0] = *(const f32x4*)(g + bj * HALF); gv[bj][1] = *(const f32x4*)(g + bj * HALF + 4); Gv[bj][0] = (f32x4){0.f, 0.f, 0.f, 0.f}; Gv[bj][1] = (f32x4){0.f, 0.f, 0.f, 0.f};
;             if (Hn) { const float* sc = scnext + (size_t)b * gate_bstride + col0 + bj * HALF;
;                 Gv[bj][0] = *(const f32x4*)(gnext + col0 + bj * HALF) * (1.0f + *(const f32x4*)(sc)); Gv[bj][1] = *(const f32x4*)(gnext + col0 + bj * HALF + 4) * (1.0f + *(const f32x4*)(sc + 4)); } }
; template <class Epi, class Sched, bool ALIGN_EPI = false, bool SP2 = false>
; __device__ __forceinline__ void gemm_phase(PG8_LAS unsigned char* lds, const Gemm g, const Sched& S, const Epi& E) {
;     ...
;             PG8_LDA(At, 1, 1); PG8_STAGE(PG8_SB(1, 0), b3, voffB); PG8_STAGE(PG8_SB(1, 1), b3 + hstep, voffB); PG8_STAGE(PG8_SA(1, 0), a3, voffA);
;             PG8_WAIT_V(8); PG8_WAIT_L(0); PG8_BAR; PG8_MMA(1, 0, At, B0); PG8_MMA(1, 1, At, B1); PG8_BAR; PG8_SCHED;
	s_add_u32 s4, s8, 0x80
	s_addc_u32 s5, s9, 0
	s_add_i32 s10, s38, s15
	ds_read_b128 v[178:181], v194 offset:49152
	ds_read_b128 v[182:185], v194 offset:50176
	ds_read_b128 v[186:189], v194 offset:51200
	ds_read_b128 v[196:199], v194 offset:52224
	ds_read_b128 v[200:203], v194 offset:53248
	ds_read_b128 v[204:207], v194 offset:54272
	ds_read_b128 v[208:211], v194 offset:55296
	ds_read_b128 v[212:215], v194 offset:56320
	s_mov_b32 m0, s10
	s_nop 0
	global_load_lds_dwordx4 v162, s[4:5]
	s_add_i32 m0, s10, 0x2000
	s_nop 0
	global_load_lds_dwordx4 v190, s[4:5]
	s_add_u32 s4, s8, 0x160080
	s_addc_u32 s5, s9, 0
	s_add_i32 s8, s39, s15
	s_mov_b32 m0, s8
	s_nop 0
	global_load_lds_dwordx4 v162, s[4:5]
	s_add_i32 m0, s8, 0x2000
	s_nop 0
	global_load_lds_dwordx4 v190, s[4:5]
	s_mov_b32 m0, s24
	s_nop 0
	global_load_lds_dwordx4 v1, s[6:7]
	s_mov_b32 m0, s25
	s_nop 0
	global_load_lds_dwordx4 v164, s[6:7]
	s_waitcnt vmcnt(8)
	s_waitcnt lgkmcnt(0)
	s_barrier
	s_setprio 1
	s_waitcnt lgkmcnt(0)
	v_mfma_f32_16x16x32_bf16 v[110:113], v[74:77], v[178:181], v[110:113]
	v_mfma_f32_16x16x32_bf16 v[94:97], v[74:77], v[186:189], v[94:97]
	v_mfma_f32_16x16x32_bf16 v[110:113], v[78:81], v[182:185], v[110:113]
	v_mfma_f32_16x16x32_bf16 v[94:97], v[78:81], v[196:199], v[94:97]
	v_mfma_f32_16x16x32_bf16 v[86:89], v[74:77], v[200:203], v[86:89]
	v_mfma_f32_16x16x32_bf16 v[34:37], v[74:77], v[208:211], v[34:37]
	v_mfma_f32_16x16x32_bf16 v[86:89], v[78:81], v[204:207], v[86:89]
	v_mfma_f32_16x16x32_bf16 v[78:81], v[78:81], v[212:215], v[34:37]
	v_mfma_f32_16x16x32_bf16 v[106:109], v[98:101], v[178:181], v[106:109]
	v_mfma_f32_16x16x32_bf16 v[90:93], v[98:101], v[186:189], v[90:93]
	v_mfma_f32_16x16x32_bf16 v[106:109], v[102:105], v[182:185], v[106:109]
	v_mfma_f32_16x16x32_bf16 v[90:93], v[102:105], v[196:199], v[90:93]
	v_mfma_f32_16x16x32_bf16 v[82:85], v[98:101], v[200:203], v[82:85]
	v_mfma_f32_16x16x32_bf16 v[34:37], v[98:101], v[208:211], v[38:41]
	v_mfma_f32_16x16x32_bf16 v[82:85], v[102:105], v[204:207], v[82:85]
	v_mfma_f32_16x16x32_bf16 v[74:77], v[102:105], v[212:215], v[34:37]
	s_setprio 0
	s_setprio 1
	v_mfma_f32_16x16x32_bf16 v[30:33], v[146:149], v[178:181], v[30:33]
	v_mfma_f32_16x16x32_bf16 v[22:25], v[146:149], v[186:189], v[22:25]
	v_mfma_f32_16x16x32_bf16 v[30:33], v[150:153], v[182:185], v[30:33]
	v_mfma_f32_16x16x32_bf16 v[22:25], v[150:153], v[196:199], v[22:25]
	v_mfma_f32_16x16x32_bf16 v[26:29], v[154:157], v[178:181], v[26:29]
	v_mfma_f32_16x16x32_bf16 v[18:21], v[154:157], v[186:189], v[18:21]
	v_mfma_f32_16x16x32_bf16 v[26:29], v[158:161], v[182:185], v[26:29]
	v_mfma_f32_16x16x32_bf16 v[18:21], v[158:161], v[196:199], v[18:21]
	v_mfma_f32_16x16x32_bf16 v[14:17], v[146:149], v[200:203], v[14:17]
	v_mfma_f32_16x16x32_bf16 v[6:9], v[146:149], v[208:211], v[6:9]
	v_mfma_f32_16x16x32_bf16 v[14:17], v[150:153], v[204:207], v[14:17]
	v_mfma_f32_16x16x32_bf16 v[6:9], v[150:153], v[212:215], v[6:9]
	v_mfma_f32_16x16x32_bf16 v[10:13], v[154:157], v[200:203], v[10:13]
	v_mfma_f32_16x16x32_bf16 v[2:5], v[154:157], v[208:211], v[2:5]
	v_mfma_f32_16x16x32_bf16 v[10:13], v[158:161], v[204:207], v[10:13]
	v_mfma_f32_16x16x32_bf16 v[2:5], v[158:161], v[212:215], v[2:5]
	s_setprio 0
	s_barrier
	s_add_i32 s35, s35, 2
	s_add_u32 s31, s31, 0x100
	s_addc_u32 s34, s34, 0
	s_cmpk_gt_u32 s35, 0x55
	s_mov_b64 s[4:5], s[2:3]
	s_cbranch_scc0 .LBB0_707
	s_ashr_i32 s2, s29, 31
	s_lshr_b32 s2, s2, 27
	s_add_i32 s2, s29, s2
	s_ashr_i32 s2, s2, 5
	v_lshl_or_b32 v156, s30, 8, v193
	s_mul_i32 s5, s2, 0xc000
	v_ashrrev_i32_e32 v157, 31, v156
	s_mul_hi_i32 s4, s2, 0xc000
	s_add_u32 s2, s20, s5
	s_addc_u32 s3, s21, s4
	v_lshlrev_b64 v[34:35], 2, v[156:157]
	v_lshl_add_u64 v[38:39], s[2:3], 0, v[34:35]
	global_load_dwordx4 v[98:101], v[38:39], off offset:16
	global_load_dwordx4 v[102:105], v[38:39], off
	s_add_u32 s2, s22, s5
	s_addc_u32 s3, s23, s4
	v_lshl_add_u64 v[148:149], s[2:3], 0, v[34:35]
	v_lshl_add_u64 v[146:147], s[48:49], 0, v[34:35]
	v_mov_b32_e32 v158, 0
	v_cndmask_b32_e64 v34, 0, 1, s[46:47]
	v_cmp_ne_u32_e64 s[2:3], 1, v34
	s_andn2_b64 vcc, exec, s[46:47]
	v_mov_b32_e32 v159, v158
	v_mov_b32_e32 v160, v158
	v_mov_b32_e32 v161, v158
	v_mov_b32_e32 v178, v158
	v_mov_b32_e32 v179, v158
	v_mov_b32_e32 v180, v158
	v_mov_b32_e32 v181, v158
	s_cbranch_vccnz .LBB0_710
	global_load_dwordx4 v[34:37], v[148:149], off
	global_load_dwordx4 v[150:153], v[148:149], off offset:16
	global_load_dwordx4 v[158:161], v[146:147], off
	global_load_dwordx4 v[178:181], v[146:147], off offset:16
	s_waitcnt vmcnt(0)
	v_pk_add_f32 v[36:37], v[36:37], 1.0 op_sel_hi:[1,0]
	v_pk_add_f32 v[34:35], v[34:35], 1.0 op_sel_hi:[1,0]
	v_pk_add_f32 v[40:41], v[152:153], 1.0 op_sel_hi:[1,0]
	v_pk_add_f32 v[150:151], v[150:151], 1.0 op_sel_hi:[1,0]
	v_pk_mul_f32 v[160:161], v[160:161], v[36:37]
	v_pk_mul_f32 v[158:159], v[158:159], v[34:35]
	v_pk_mul_f32 v[180:181], v[180:181], v[40:41]
	v_pk_mul_f32 v[178:179], v[178:179], v[150:151]
